# bundle on rs-cache version: GEMM phase prologues issue both LDS-DMA stage groups before the first wait (9 phases), late epilogue-align barrier (P1/P3/P7), tile-start vmcnt(0) dropped in P5a/P5b/P6/P7
# speedup vs baseline: 1.0051x; 1.0003x over previous
; #define PG8_STAGE(bufoff, gbase, voff) do { _Pragma("unroll") for (int _i = 0; _i < 2; ++_i) \
;         __builtin_amdgcn_global_load_lds((const unsigned*)((const char*)(gbase) + (voff)[_i]), (LAS unsigned*)(lds + (bufoff) + ldsw + _i * 8192), 16, 0, 0); } while (0)
; #define PG8_WAIT_V(n) asm volatile("s_waitcnt vmcnt(" #n ")" ::: "memory")
; #define PG8_BAR __builtin_amdgcn_s_barrier()
; template <class Epi>
; __device__ __forceinline__ void gemm_phase(LAS unsigned char* lds, const Gemm g, const StaticOrder& S, const Epi& E) {
;     ...
;     const size_t aslab = g.aslab ? g.aslab : 32 * tstepA;
;     const char* cA = (const char*)g.A + (size_t)(cur.pm >> 5) * aslab + (size_t)(cur.pm & 31) * tstepA; const char* cB = (const char*)g.Bt + (size_t)cur.pn * tstepB;
;     PG8_STAGE(PG8_SB(0, 0), cB, voffB); PG8_STAGE(PG8_SB(0, 1), cB + hstepB, voffB); PG8_STAGE(PG8_SA(0, 0), cA, voffA); PG8_STAGE(PG8_SA(0, 1), cA + hstepA, voffA);
;     if (wr == 1) PG8_BAR;
;     PG8_WAIT_V(2); PG8_BAR;
;     PG8_STAGE(PG8_SB(1, 0), cB + kstep, voffB); PG8_STAGE(PG8_SA(1, 0), cA + kstep, voffA); PG8_STAGE(PG8_SB(1, 1), cB + hstepB + kstep, voffB);
;     PG8_WAIT_V(6); PG8_BAR;
.LBB0_147:
	s_lshl_b32 s14, s14, 5
	s_lshl_b32 s48, s15, 6
	s_lshl_b32 s19, s15, 13
	s_and_b32 s20, s14, 0x60
	s_mov_b64 s[14:15], 0x80
	s_add_i32 m0, s42, 0x18000
	v_lshl_add_u64 v[6:7], v[6:7], 0, s[14:15]
	s_lshl_b32 s21, s20, 7
	global_load_lds_dwordx4 v[6:7], off
	v_lshl_add_u64 v[2:3], v[2:3], 0, s[14:15]
	s_add_i32 m0, s42, 0x1a000
	s_add_i32 s49, s42, 0x8000
	s_add_i32 s50, s42, 0xa000
	global_load_lds_dwordx4 v[2:3], off
	v_lshl_add_u64 v[0:1], v[0:1], 0, s[14:15]
	s_mov_b32 m0, s49
	s_add_u32 s16, s2, 0x40080
	global_load_lds_dwordx4 v[0:1], off
	v_lshl_add_u64 v[0:1], v[4:5], 0, s[14:15]
	s_mov_b32 m0, s50
	s_addc_u32 s17, s3, 0
	global_load_lds_dwordx4 v[0:1], off
	s_add_i32 m0, s42, 0x1c000
	v_lshl_add_u64 v[0:1], s[16:17], 0, v[128:129]
	global_load_lds_dwordx4 v[0:1], off
	v_lshl_add_u64 v[0:1], s[16:17], 0, v[130:131]
	s_add_i32 m0, s42, 0x1e000
	v_and_b32_e32 v146, 15, v8
	global_load_lds_dwordx4 v[0:1], off
	s_waitcnt vmcnt(8)
	s_barrier
	v_lshrrev_b32_e32 v0, 1, v8
	v_and_b32_e32 v0, 24, v0
	v_lshlrev_b32_e32 v1, 1, v0
	v_lshlrev_b32_e32 v2, 2, v8
	v_or_b32_e32 v148, s20, v0
	v_lshlrev_b32_e32 v0, 14, v13
	v_lshl_or_b32 v1, v146, 6, v1
	v_and_b32_e32 v2, 32, v2
	v_and_b32_e32 v0, 0xffff8000, v0
	v_bitop3_b32 v3, v1, s19, v2 bitop3:0xde
	v_bitop3_b32 v147, v1, s21, v2 bitop3:0xde
	v_lshl_add_u32 v0, v12, 11, v0
	v_and_b32_e32 v1, 1, v13
	v_lshl_or_b32 v0, v1, 6, v0
	s_cmpk_lt_u32 s1, 0x100
	v_lshl_add_u32 v136, v14, 1, v0
	v_lshlrev_b32_e32 v0, 14, v9
	s_sext_i32_i16 s57, s0
	s_cselect_b64 s[16:17], -1, 0
	s_ashr_i32 s51, s74, 31
	v_readlane_b32 s0, v235, 0
	v_and_b32_e32 v0, 0xffff8000, v0
	s_waitcnt vmcnt(6)
	s_sub_u32 s0, 0x1600, s0
	v_lshl_add_u32 v0, v10, 11, v0
	v_and_b32_e32 v1, 1, v9
	s_subb_u32 s1, 0, s18
	v_mov_b32_e32 v139, 0
	v_lshl_or_b32 v0, v1, 6, v0
	s_add_i32 s53, 0, 0x10000
	s_add_i32 s54, 0, 0x14000
	s_mov_b32 s52, s74
	v_mov_b32_e32 v137, v139
	v_lshl_add_u32 v140, v11, 1, v0
	v_mov_b32_e32 v141, v139
	v_mov_b64_e32 v[142:143], s[0:1]
	v_add_u32_e32 v149, s53, v147
	v_add_u32_e32 v150, s54, v147
	v_add_u32_e32 v151, 0, v3
	v_mov_b32_e32 v152, 0x358637bd
	s_mov_b32 s55, 0x2d000
	v_mov_b32_e32 v153, 0x1fcf
	s_barrier
	s_branch .LBB0_150

; #define PG8_STAGE(bufoff, gbase, voff) do { _Pragma("unroll") for (int _i = 0; _i < 2; ++_i) \
;         __builtin_amdgcn_global_load_lds((const unsigned*)((const char*)(gbase) + (voff)[_i]), (LAS unsigned*)(lds + (bufoff) + ldsw + _i * 8192), 16, 0, 0); } while (0)
; #define PG8_WAIT_V(n) asm volatile("s_waitcnt vmcnt(" #n ")" ::: "memory")
; #define PG8_BAR __builtin_amdgcn_s_barrier()
; template <class Epi>
; __device__ __forceinline__ void gemm_phase(LAS unsigned char* lds, const Gemm g, const StaticOrder& S, const Epi& E) {
;     ...
;     const size_t aslab = g.aslab ? g.aslab : 32 * tstepA;
;     const char* cA = (const char*)g.A + (size_t)(cur.pm >> 5) * aslab + (size_t)(cur.pm & 31) * tstepA; const char* cB = (const char*)g.Bt + (size_t)cur.pn * tstepB;
;     PG8_STAGE(PG8_SB(0, 0), cB, voffB); PG8_STAGE(PG8_SB(0, 1), cB + hstepB, voffB); PG8_STAGE(PG8_SA(0, 0), cA, voffA); PG8_STAGE(PG8_SA(0, 1), cA + hstepA, voffA);
;     if (wr == 1) PG8_BAR;
;     PG8_WAIT_V(2); PG8_BAR;
;     PG8_STAGE(PG8_SB(1, 0), cB + kstep, voffB); PG8_STAGE(PG8_SA(1, 0), cA + kstep, voffA); PG8_STAGE(PG8_SB(1, 1), cB + hstepB + kstep, voffB);
;     PG8_WAIT_V(6); PG8_BAR;
.LBB0_243:
	s_mov_b64 s[20:21], 0x80
	s_and_b32 s39, s1, 3
	s_add_i32 m0, s35, 0x18000
	v_lshl_add_u64 v[6:7], v[6:7], 0, s[20:21]
	s_lshl_b32 s1, s5, 13
	s_lshl_b32 s24, s39, 12
	global_load_lds_dwordx4 v[6:7], off
	v_lshl_add_u64 v[4:5], v[4:5], 0, s[20:21]
	s_add_i32 m0, s35, 0x1a000
	s_add_i32 s40, s35, 0x8000
	s_add_i32 s41, s35, 0xa000
	global_load_lds_dwordx4 v[4:5], off
	v_lshl_add_u64 v[0:1], v[0:1], 0, s[20:21]
	s_mov_b32 m0, s40
	s_add_u32 s6, s8, 0xb0080
	global_load_lds_dwordx4 v[0:1], off
	v_lshl_add_u64 v[0:1], v[2:3], 0, s[20:21]
	s_mov_b32 m0, s41
	s_addc_u32 s7, s9, 0
	global_load_lds_dwordx4 v[0:1], off
	s_add_i32 m0, s35, 0x1c000
	v_lshl_add_u64 v[0:1], s[6:7], 0, v[154:155]
	global_load_lds_dwordx4 v[0:1], off
	v_lshl_add_u64 v[0:1], s[6:7], 0, v[158:159]
	s_add_i32 m0, s35, 0x1e000
	s_cmpk_lt_u32 s4, 0x100
	global_load_lds_dwordx4 v[0:1], off
	s_waitcnt vmcnt(8)
	s_barrier
	v_and_b32_e32 v1, 15, v8
	v_lshl_or_b32 v184, s5, 6, v1
	v_readlane_b32 s5, v235, 0
	s_cselect_b64 s[22:23], -1, 0
	s_ashr_i32 s42, s74, 31
	s_ashr_i32 s4, s5, 31
	s_sub_u32 s6, 0x400, s5
	s_subb_u32 s7, 0, s4
	s_abs_i32 s25, s74
	v_bfe_u32 v0, v8, 4, 2
	v_cvt_f32_u32_e32 v4, s25
	v_lshlrev_b32_e32 v3, 4, v0
	v_lshl_or_b32 v1, v1, 6, v3
	v_lshlrev_b32_e32 v3, 2, v8
	v_and_b32_e32 v3, 32, v3
	v_bitop3_b32 v5, v1, s1, v3 bitop3:0xde
	v_bitop3_b32 v185, v1, s24, v3 bitop3:0xde
	v_rcp_iflag_f32_e32 v1, v4
	s_sub_i32 s1, 0, s25
	v_lshlrev_b32_e32 v2, 3, v0
	v_cmp_eq_u32_e64 s[4:5], 0, v0
	v_mul_f32_e32 v1, 0x4f7ffffe, v1
	v_cvt_u32_f32_e32 v1, v1
	v_mul_lo_u32 v0, v11, s0
	s_waitcnt vmcnt(6)
	v_lshl_or_b32 v186, s39, 5, v2
	v_readfirstlane_b32 s24, v1
	s_mul_i32 s1, s1, s24
	s_mul_hi_u32 s1, s24, s1
	s_add_i32 s24, s24, s1
	s_lshr_b32 s1, s24, 22
	s_mul_i32 s24, s1, s25
	s_sub_i32 s24, 0x400, s24
	s_add_i32 s26, s1, 1
	s_sub_i32 s27, s24, s25
	s_cmp_ge_u32 s24, s25
	s_cselect_b32 s1, s26, s1
	s_cselect_b32 s24, s27, s24
	s_add_i32 s26, s1, 1
	s_cmp_ge_u32 s24, s25
	s_cselect_b32 s1, s26, s1
	s_xor_b32 s1, s1, s42
	s_sub_i32 s44, s1, s42
	v_lshrrev_b32_e32 v1, 1, v9
	s_mov_b32 s1, 0xb400
	v_mad_u64_u32 v[0:1], s[24:25], v1, s1, v[0:1]
	v_or_b32_e32 v0, v0, v10
	v_add_lshl_u32 v0, v0, v12, 1
	v_mov_b32_e32 v1, v155
	s_mov_b64 s[24:25], 0xb4080
	v_lshl_add_u64 v[160:161], v[0:1], 0, s[24:25]
	v_lshrrev_b32_e32 v1, 1, v13
	v_mul_lo_u32 v0, v14, s0
	v_mad_u64_u32 v[0:1], s[0:1], v1, s1, v[0:1]
	v_or_b32_e32 v0, v0, v15
	v_add_lshl_u32 v0, v0, v16, 1
	v_mov_b32_e32 v1, v155
	v_lshl_add_u64 v[162:163], v[0:1], 0, s[24:25]
	s_add_i32 s45, 0, 0x10000
	s_add_i32 s46, 0, 0x14000
	v_mbcnt_lo_u32_b32 v0, -1, 0
	s_mov_b32 s43, s74
	v_mov_b64_e32 v[164:165], s[6:7]
	v_add_u32_e32 v187, s45, v185
	v_add_u32_e32 v188, s46, v185
	v_add_u32_e32 v190, 0, v5
	v_mbcnt_hi_u32_b32 v191, -1, v0
	s_mov_b32 s6, 0
	s_barrier
	s_branch .LBB0_246

; #define PG8_STAGE(bufoff, gbase, voff) do { _Pragma("unroll") for (int _i = 0; _i < 2; ++_i) \
;         __builtin_amdgcn_global_load_lds((const unsigned*)((const char*)(gbase) + (voff)[_i]), (LAS unsigned*)(lds + (bufoff) + ldsw + _i * 8192), 16, 0, 0); } while (0)
; #define PG8_WAIT_V(n) asm volatile("s_waitcnt vmcnt(" #n ")" ::: "memory")
; #define PG8_BAR __builtin_amdgcn_s_barrier()
; template <class Epi>
; __device__ __forceinline__ void gemm_phase(LAS unsigned char* lds, const Gemm g, const StaticOrder& S, const Epi& E) {
;     ...
;     const size_t aslab = g.aslab ? g.aslab : 32 * tstepA;
;     const char* cA = (const char*)g.A + (size_t)(cur.pm >> 5) * aslab + (size_t)(cur.pm & 31) * tstepA; const char* cB = (const char*)g.Bt + (size_t)cur.pn * tstepB;
;     PG8_STAGE(PG8_SB(0, 0), cB, voffB); PG8_STAGE(PG8_SB(0, 1), cB + hstepB, voffB); PG8_STAGE(PG8_SA(0, 0), cA, voffA); PG8_STAGE(PG8_SA(0, 1), cA + hstepA, voffA);
;     if (wr == 1) PG8_BAR;
;     PG8_WAIT_V(2); PG8_BAR;
;     PG8_STAGE(PG8_SB(1, 0), cB + kstep, voffB); PG8_STAGE(PG8_SA(1, 0), cA + kstep, voffA); PG8_STAGE(PG8_SB(1, 1), cB + hstepB + kstep, voffB);
;     PG8_WAIT_V(6); PG8_BAR;
.LBB0_373:
	s_lshl_b32 s6, s6, 5
	s_and_b32 s17, s6, 0x60
	s_mov_b64 s[6:7], 0x80
	s_add_i32 m0, s28, 0x18000
	v_lshl_add_u64 v[6:7], v[6:7], 0, s[6:7]
	s_lshl_b32 s9, s8, 13
	s_lshl_b32 s20, s17, 7
	global_load_lds_dwordx4 v[6:7], off
	v_lshl_add_u64 v[4:5], v[4:5], 0, s[6:7]
	s_add_i32 m0, s28, 0x1a000
	s_add_i32 s35, s28, 0x8000
	s_add_i32 s36, s28, 0xa000
	global_load_lds_dwordx4 v[4:5], off
	v_lshl_add_u64 v[0:1], v[0:1], 0, s[6:7]
	s_mov_b32 m0, s35
	s_add_u32 s18, s2, 0x40080
	global_load_lds_dwordx4 v[0:1], off
	v_lshl_add_u64 v[0:1], v[2:3], 0, s[6:7]
	s_mov_b32 m0, s36
	s_addc_u32 s19, s3, 0
	global_load_lds_dwordx4 v[0:1], off
	s_add_i32 m0, s28, 0x1c000
	v_lshl_add_u64 v[0:1], s[18:19], 0, v[156:157]
	global_load_lds_dwordx4 v[0:1], off
	v_lshl_add_u64 v[0:1], s[18:19], 0, v[152:153]
	s_add_i32 m0, s28, 0x1e000
	v_lshlrev_b32_e32 v2, 2, v10
	global_load_lds_dwordx4 v[0:1], off
	s_waitcnt vmcnt(8)
	s_barrier
	v_bfe_u32 v1, v10, 4, 2
	v_and_b32_e32 v0, 15, v10
	v_lshlrev_b32_e32 v160, 4, v1
	v_lshl_or_b32 v193, s8, 6, v0
	v_lshl_or_b32 v0, v0, 6, v160
	v_and_b32_e32 v2, 32, v2
	v_bitop3_b32 v3, v0, s9, v2 bitop3:0xde
	v_bitop3_b32 v195, v0, s20, v2 bitop3:0xde
	v_lshlrev_b32_e32 v0, 14, v13
	v_and_b32_e32 v0, 0xffff8000, v0
	v_lshl_or_b32 v197, v1, 3, s17
	v_lshl_add_u32 v0, v12, 11, v0
	v_and_b32_e32 v1, 1, v13
	v_lshl_or_b32 v0, v1, 6, v0
	s_sext_i32_i16 s43, s4
	s_cmpk_lt_u32 s5, 0x100
	v_readlane_b32 s4, v235, 50
	v_lshl_add_u32 v164, v14, 1, v0
	v_lshlrev_b32_e32 v0, 14, v8
	v_readlane_b32 s5, v235, 51
	v_and_b32_e32 v0, 0xffff8000, v0
	s_cselect_b64 s[8:9], -1, 0
	v_lshl_add_u64 v[162:163], s[4:5], 0, v[160:161]
	s_ashr_i32 s37, s74, 31
	v_readlane_b32 s4, v235, 0
	v_lshl_add_u32 v0, v9, 11, v0
	v_and_b32_e32 v1, 1, v8
	s_waitcnt vmcnt(6)
	s_sub_u32 s4, 0x1100, s4
	v_lshl_or_b32 v0, v1, 6, v0
	s_subb_u32 s5, 0, s16
	v_lshl_add_u32 v166, v11, 1, v0
	s_add_i32 s39, 0, 0x10000
	s_add_i32 s40, 0, 0x14000
	v_mbcnt_lo_u32_b32 v0, -1, 0
	s_mov_b32 s38, s74
	v_mov_b32_e32 v165, v161
	v_mov_b32_e32 v167, v161
	v_mov_b64_e32 v[168:169], s[4:5]
	v_add_u32_e32 v198, s39, v195
	v_add_u32_e32 v199, s40, v195
	v_add_u32_e32 v200, 0, v3
	v_mbcnt_hi_u32_b32 v201, -1, v0
	v_mov_b32_e32 v202, 0x358637bd
	s_movk_i32 s41, 0x2200
	s_barrier
	s_branch .LBB0_376

; #define PG8_STAGE(bufoff, gbase, voff) do { _Pragma("unroll") for (int _i = 0; _i < 2; ++_i) \
;         __builtin_amdgcn_global_load_lds((const unsigned*)((const char*)(gbase) + (voff)[_i]), (LAS unsigned*)(lds + (bufoff) + ldsw + _i * 8192), 16, 0, 0); } while (0)
; #define PG8_WAIT_V(n) asm volatile("s_waitcnt vmcnt(" #n ")" ::: "memory")
; #define PG8_BAR __builtin_amdgcn_s_barrier()
; template <class Epi>
; __device__ __forceinline__ void gemm_phase(LAS unsigned char* lds, const Gemm g, const StaticOrder& S, const Epi& E) {
;     ...
;     const size_t aslab = g.aslab ? g.aslab : 32 * tstepA;
;     const char* cA = (const char*)g.A + (size_t)(cur.pm >> 5) * aslab + (size_t)(cur.pm & 31) * tstepA; const char* cB = (const char*)g.Bt + (size_t)cur.pn * tstepB;
;     PG8_STAGE(PG8_SB(0, 0), cB, voffB); PG8_STAGE(PG8_SB(0, 1), cB + hstepB, voffB); PG8_STAGE(PG8_SA(0, 0), cA, voffA); PG8_STAGE(PG8_SA(0, 1), cA + hstepA, voffA);
;     if (wr == 1) PG8_BAR;
;     PG8_WAIT_V(2); PG8_BAR;
;     PG8_STAGE(PG8_SB(1, 0), cB + kstep, voffB); PG8_STAGE(PG8_SA(1, 0), cA + kstep, voffA); PG8_STAGE(PG8_SB(1, 1), cB + hstepB + kstep, voffB);
;     PG8_WAIT_V(6); PG8_BAR;
.LBB0_687:
	s_lshl_b32 s8, s8, 5
	s_and_b32 s15, s8, 0x60
	s_mov_b64 s[8:9], 0x80
	s_add_i32 m0, s23, 0x18000
	v_lshl_add_u64 v[6:7], v[6:7], 0, s[8:9]
	s_lshl_b32 s14, s11, 13
	s_lshl_b32 s16, s15, 7
	global_load_lds_dwordx4 v[6:7], off
	v_lshl_add_u64 v[4:5], v[4:5], 0, s[8:9]
	s_add_i32 m0, s23, 0x1a000
	s_add_i32 s30, s23, 0x8000
	s_add_i32 s31, s23, 0xa000
	global_load_lds_dwordx4 v[4:5], off
	v_lshl_add_u64 v[0:1], v[0:1], 0, s[8:9]
	s_mov_b32 m0, s30
	s_add_u32 s12, s2, 0x20080
	global_load_lds_dwordx4 v[0:1], off
	v_lshl_add_u64 v[0:1], v[2:3], 0, s[8:9]
	s_mov_b32 m0, s31
	s_addc_u32 s13, s3, 0
	global_load_lds_dwordx4 v[0:1], off
	s_add_i32 m0, s23, 0x1c000
	v_lshl_add_u64 v[0:1], s[12:13], 0, v[130:131]
	global_load_lds_dwordx4 v[0:1], off
	v_lshl_add_u64 v[0:1], s[12:13], 0, v[134:135]
	s_add_i32 m0, s23, 0x1e000
	s_cmpk_lt_u32 s10, 0x100
	global_load_lds_dwordx4 v[0:1], off
	s_waitcnt vmcnt(8)
	s_barrier
	v_lshrrev_b32_e32 v1, 1, v8
	v_and_b32_e32 v1, 24, v1
	v_and_b32_e32 v0, 15, v8
	v_lshlrev_b32_e32 v2, 1, v1
	v_lshl_or_b32 v148, s11, 6, v0
	v_lshl_or_b32 v0, v0, 6, v2
	v_lshlrev_b32_e32 v2, 2, v8
	v_and_b32_e32 v2, 32, v2
	v_bitop3_b32 v3, v0, s14, v2 bitop3:0xde
	v_bitop3_b32 v149, v0, s16, v2 bitop3:0xde
	v_lshlrev_b32_e32 v0, 14, v9
	v_and_b32_e32 v0, 0xffff8000, v0
	v_or_b32_e32 v150, s15, v1
	v_lshl_add_u32 v0, v10, 11, v0
	v_and_b32_e32 v1, 1, v9
	v_lshl_or_b32 v0, v1, 6, v0
	v_lshl_add_u32 v136, v11, 1, v0
	v_lshlrev_b32_e32 v0, 14, v12
	s_sext_i32_i8 s40, s4
	s_cselect_b64 s[10:11], -1, 0
	s_ashr_i32 s33, s74, 31
	v_readlane_b32 s4, v235, 0
	v_and_b32_e32 v0, 0xffff8000, v0
	s_waitcnt vmcnt(6)
	s_sub_u32 s4, 0x400, s4
	v_lshl_add_u32 v0, v13, 11, v0
	v_and_b32_e32 v1, 1, v12
	s_subb_u32 s5, 0, s5
	v_lshl_or_b32 v0, v1, 6, v0
	s_add_i32 s35, 0, 0x10000
	s_add_i32 s36, 0, 0x14000
	s_mov_b32 s34, s74
	v_mov_b32_e32 v137, v131
	v_lshl_add_u32 v138, v14, 1, v0
	v_mov_b32_e32 v139, v131
	v_mov_b64_e32 v[140:141], s[4:5]
	v_add_u32_e32 v151, s35, v149
	v_add_u32_e32 v152, s36, v149
	v_add_u32_e32 v153, 0, v3
	s_movk_i32 s37, 0x2200
	s_barrier
	s_branch .LBB0_690

; #define PG8_STAGE(bufoff, gbase, voff) do { _Pragma("unroll") for (int _i = 0; _i < 2; ++_i) \
;         __builtin_amdgcn_global_load_lds((const unsigned*)((const char*)(gbase) + (voff)[_i]), (LAS unsigned*)(lds + (bufoff) + ldsw + _i * 8192), 16, 0, 0); } while (0)
; #define PG8_LDA(dst, b, h) do { _Pragma("unroll") for (int m = 0; m < 4; ++m) _Pragma("unroll") for (int k = 0; k < 2; ++k) dst[m][k] = *(const LAS bf16x8*)(lds + PG8_SA(b, h) + aoff + m * 2048 + k * 1024); } while (0)
; #define PG8_LDB(dst, b, h) do { _Pragma("unroll") for (int n = 0; n < 2; ++n) _Pragma("unroll") for (int k = 0; k < 2; ++k) dst[n][k] = *(const LAS bf16x8*)(lds + PG8_SB(b, h) + boff + n * 2048 + k * 1024); } while (0)
; #define PG8_MMA(ai, bj, At, Bt) do { __builtin_amdgcn_s_setprio(1); _Pragma("unroll") for (int m = 0; m < 4; ++m) _Pragma("unroll") for (int n = 0; n < 2; ++n) _Pragma("unroll") for (int k = 0; k < 2; ++k) \
;         acc[ai][bj][m][n] = __builtin_amdgcn_mfma_f32_16x16x32_bf16(Bt[n][k], At[m][k], acc[ai][bj][m][n], 0, 0, 0); __builtin_amdgcn_s_setprio(0); } while (0)
; template <class Epi>
; __device__ __forceinline__ void gemm_phase(LAS unsigned char* lds, const Gemm g, const StaticOrder& S, const Epi& E) {
;     ...
;         const bool has_next = S.next(ui + 1, nxt);
;         const char* nA = has_next ? (const char*)g.A + (size_t)(nxt.pm >> 5) * aslab + (size_t)(nxt.pm & 31) * tstepA : cA; const char* nB = has_next ? (const char*)g.Bt + (size_t)nxt.pn * tstepB : cB;
;         for (int t = 0; t < nt; t += 2) {
;             const bool last = (t == nt - 2);
;             const char* a1 = cA + (size_t)(t + 1) * kstep;
;             const char* a2 = last ? nA : cA + (size_t)(t + 2) * kstep; const char* b2 = last ? nB : cB + (size_t)(t + 2) * kstep;
;             const char* a3 = a2 + kstep; const char* b3 = b2 + kstep;
;             PG8_LDB(B0, 0, 0); PG8_LDB(B1, 0, 1); PG8_SCHED; PG8_LDA(At, 0, 0); PG8_STAGE(PG8_SA(1, 1), a1 + hstepA, voffA);
;             PG8_WAIT_V(8); PG8_WAIT_L(0); PG8_BAR; PG8_MMA(0, 0, At, B0); PG8_MMA(0, 1, At, B1); PG8_BAR; PG8_SCHED;
;             PG8_LDA(At, 0, 1); PG8_STAGE(PG8_SB(0, 0), b2, voffB); PG8_STAGE(PG8_SB(0, 1), b2 + hstepB, voffB); PG8_STAGE(PG8_SA(0, 0), a2, voffA);
;             PG8_WAIT_V(8); PG8_WAIT_L(0); PG8_BAR; PG8_MMA(1, 0, At, B0); PG8_MMA(1, 1, At, B1); PG8_BAR; PG8_SCHED;
.LBB0_696:
	s_ashr_i32 s14, s38, 5
	s_ashr_i32 s15, s14, 31
	s_lshl_b64 s[14:15], s[14:15], 24
	s_add_u32 s13, s24, s14
	s_addc_u32 s15, s25, s15
	s_lshl_b32 s14, s38, 19
	s_and_b32 s14, s14, 0xf80000
	s_add_u32 s14, s13, s14
	s_addc_u32 s15, s15, 0
	s_and_b64 s[16:17], s[4:5], exec
	s_cselect_b32 s41, s15, s19
	s_cselect_b32 s42, s14, s18
	s_ashr_i32 s13, s12, 31
	s_lshl_b64 s[16:17], s[12:13], 18
	v_readlane_b32 s20, v235, 25
	v_readlane_b32 s21, v235, 26
	s_add_u32 s16, s20, s16
	s_addc_u32 s17, s21, s17
	s_and_b64 s[20:21], s[4:5], exec
	s_cselect_b32 s13, s17, s3
	s_cselect_b32 s43, s16, s2
	s_add_u32 s18, s18, 0x40080
	s_addc_u32 s19, s19, 0
	s_add_u32 s44, s2, 0x100
	s_addc_u32 s45, s3, 0
	s_mov_b32 s46, -2
	ds_read_b128 v[142:145], v151
	ds_read_b128 v[154:157], v151 offset:1024
	ds_read_b128 v[158:161], v151 offset:2048
	ds_read_b128 v[162:165], v151 offset:3072
	ds_read_b128 v[166:169], v152
	ds_read_b128 v[170:173], v152 offset:1024
	ds_read_b128 v[174:177], v152 offset:2048
	ds_read_b128 v[178:181], v152 offset:3072
	s_add_u32 s2, s18, 0xfffc0080
	s_addc_u32 s3, s19, -1
	s_cmp_eq_u32 s46, 4
	s_cselect_b32 s21, s41, s3
	s_cselect_b32 s20, s42, s2
	s_cselect_b32 s3, s13, s45
	s_cselect_b32 s2, s43, s44
	v_lshl_add_u64 v[146:147], s[18:19], 0, v[136:137]
	s_add_i32 m0, s23, 0xc000
	ds_read_b128 v[182:185], v153
	ds_read_b128 v[190:193], v153 offset:1024
	ds_read_b128 v[198:201], v153 offset:2048
	ds_read_b128 v[202:205], v153 offset:3072
	ds_read_b128 v[206:209], v153 offset:4096
	ds_read_b128 v[210:213], v153 offset:5120
	ds_read_b128 v[214:217], v153 offset:6144
	ds_read_b128 v[218:221], v153 offset:7168
	global_load_lds_dwordx4 v[146:147], off
	v_lshl_add_u64 v[146:147], s[18:19], 0, v[138:139]
	s_add_i32 m0, s23, 0xe000
	s_nop 0
	global_load_lds_dwordx4 v[146:147], off
	s_waitcnt vmcnt(8)
	s_waitcnt lgkmcnt(0)
	s_barrier
	s_waitcnt lgkmcnt(0)
	v_mfma_f32_16x16x32_bf16 v[124:127], v[142:145], v[182:185], 0
	v_mfma_f32_16x16x32_bf16 v[120:123], v[158:161], v[182:185], 0
	v_mfma_f32_16x16x32_bf16 v[116:119], v[142:145], v[198:201], 0
	v_mfma_f32_16x16x32_bf16 v[112:115], v[158:161], v[198:201], 0
	v_mfma_f32_16x16x32_bf16 v[96:99], v[142:145], v[206:209], 0
	v_mfma_f32_16x16x32_bf16 v[88:91], v[158:161], v[206:209], 0
	v_mfma_f32_16x16x32_bf16 v[80:83], v[142:145], v[214:217], 0
	v_mfma_f32_16x16x32_bf16 v[72:75], v[158:161], v[214:217], 0
	v_mfma_f32_16x16x32_bf16 v[124:127], v[154:157], v[190:193], v[124:127]
	v_mfma_f32_16x16x32_bf16 v[120:123], v[162:165], v[190:193], v[120:123]
	v_mfma_f32_16x16x32_bf16 v[116:119], v[154:157], v[202:205], v[116:119]
	v_mfma_f32_16x16x32_bf16 v[112:115], v[162:165], v[202:205], v[112:115]
	v_mfma_f32_16x16x32_bf16 v[96:99], v[154:157], v[210:213], v[96:99]
	v_mfma_f32_16x16x32_bf16 v[88:91], v[162:165], v[210:213], v[88:91]
	v_mfma_f32_16x16x32_bf16 v[80:83], v[154:157], v[218:221], v[80:83]
	v_mfma_f32_16x16x32_bf16 v[72:75], v[162:165], v[218:221], v[72:75]
	v_mfma_f32_16x16x32_bf16 v[108:111], v[166:169], v[182:185], 0
	v_mfma_f32_16x16x32_bf16 v[104:107], v[174:177], v[182:185], 0
	v_mfma_f32_16x16x32_bf16 v[100:103], v[166:169], v[198:201], 0
	v_mfma_f32_16x16x32_bf16 v[92:95], v[174:177], v[198:201], 0
	v_mfma_f32_16x16x32_bf16 v[84:87], v[166:169], v[206:209], 0
	v_mfma_f32_16x16x32_bf16 v[76:79], v[174:177], v[206:209], 0
	v_mfma_f32_16x16x32_bf16 v[68:71], v[166:169], v[214:217], 0
	v_mfma_f32_16x16x32_bf16 v[64:67], v[174:177], v[214:217], 0
	v_mfma_f32_16x16x32_bf16 v[108:111], v[170:173], v[190:193], v[108:111]
	v_mfma_f32_16x16x32_bf16 v[104:107], v[178:181], v[190:193], v[104:107]
	v_mfma_f32_16x16x32_bf16 v[100:103], v[170:173], v[202:205], v[100:103]
	v_mfma_f32_16x16x32_bf16 v[92:95], v[178:181], v[202:205], v[92:95]
	v_mfma_f32_16x16x32_bf16 v[84:87], v[170:173], v[210:213], v[84:87]
	v_mfma_f32_16x16x32_bf16 v[76:79], v[178:181], v[210:213], v[76:79]
	v_mfma_f32_16x16x32_bf16 v[68:71], v[170:173], v[218:221], v[68:71]
	v_mfma_f32_16x16x32_bf16 v[64:67], v[178:181], v[218:221], v[64:67]
	s_barrier
	s_add_i32 s47, s35, s22
	v_lshl_add_u64 v[146:147], s[2:3], 0, v[130:131]
	s_mov_b32 m0, s47
	ds_read_b128 v[182:185], v153 offset:16384
	ds_read_b128 v[190:193], v153 offset:17408
	ds_read_b128 v[198:201], v153 offset:18432
	ds_read_b128 v[202:205], v153 offset:19456
	ds_read_b128 v[206:209], v153 offset:20480
	ds_read_b128 v[210:213], v153 offset:21504
	ds_read_b128 v[214:217], v153 offset:22528
	ds_read_b128 v[218:221], v153 offset:23552
	global_load_lds_dwordx4 v[146:147], off
	s_add_i32 m0, s47, 0x2000
	s_add_u32 s48, s2, 0x20000
	v_lshl_add_u64 v[186:187], s[2:3], 0, v[134:135]
	s_addc_u32 s49, s3, 0
	s_add_i32 s47, s36, s22
	global_load_lds_dwordx4 v[186:187], off
	v_lshl_add_u64 v[194:195], s[48:49], 0, v[130:131]
	s_mov_b32 m0, s47
	v_lshl_add_u64 v[222:223], s[20:21], 0, v[132:133]
	global_load_lds_dwordx4 v[194:195], off
	v_lshl_add_u64 v[194:195], s[48:49], 0, v[134:135]
	s_add_i32 m0, s47, 0x2000
	s_nop 0
	global_load_lds_dwordx4 v[194:195], off
	v_lshl_add_u64 v[194:195], s[20:21], 0, v[128:129]
	s_mov_b32 m0, s23
	s_nop 0
	global_load_lds_dwordx4 v[194:195], off
	s_mov_b32 m0, s26
	s_nop 0
	global_load_lds_dwordx4 v[222:223], off
	s_waitcnt vmcnt(8)
	s_waitcnt lgkmcnt(0)
	s_barrier
; #define PG8_STAGE(bufoff, gbase, voff) do { _Pragma("unroll") for (int _i = 0; _i < 2; ++_i) \
;         __builtin_amdgcn_global_load_lds((const unsigned*)((const char*)(gbase) + (voff)[_i]), (LAS unsigned*)(lds + (bufoff) + ldsw + _i * 8192), 16, 0, 0); } while (0)
; #define PG8_LDA(dst, b, h) do { _Pragma("unroll") for (int m = 0; m < 4; ++m) _Pragma("unroll") for (int k = 0; k < 2; ++k) dst[m][k] = *(const LAS bf16x8*)(lds + PG8_SA(b, h) + aoff + m * 2048 + k * 1024); } while (0)
; #define PG8_LDB(dst, b, h) do { _Pragma("unroll") for (int n = 0; n < 2; ++n) _Pragma("unroll") for (int k = 0; k < 2; ++k) dst[n][k] = *(const LAS bf16x8*)(lds + PG8_SB(b, h) + boff + n * 2048 + k * 1024); } while (0)
; #define PG8_MMA(ai, bj, At, Bt) do { __builtin_amdgcn_s_setprio(1); _Pragma("unroll") for (int m = 0; m < 4; ++m) _Pragma("unroll") for (int n = 0; n < 2; ++n) _Pragma("unroll") for (int k = 0; k < 2; ++k) \
;         acc[ai][bj][m][n] = __builtin_amdgcn_mfma_f32_16x16x32_bf16(Bt[n][k], At[m][k], acc[ai][bj][m][n], 0, 0, 0); __builtin_amdgcn_s_setprio(0); } while (0)
; #define PG8_WAIT_V(n) asm volatile("s_waitcnt vmcnt(" #n ")" ::: "memory")
; #define PG8_WAIT_L(n) asm volatile("s_waitcnt lgkmcnt(" #n ")" ::: "memory")
; #define PG8_BAR __builtin_amdgcn_s_barrier()
; #define PG8_SCHED __builtin_amdgcn_sched_barrier(0)
; template <class Epi>
; __device__ __forceinline__ void gemm_phase(LAS unsigned char* lds, const Gemm g, const StaticOrder& S, const Epi& E) {
;     ...
;             PG8_WAIT_V(8); PG8_WAIT_L(0); PG8_BAR; PG8_MMA(1, 0, At, B0); PG8_MMA(1, 1, At, B1); PG8_BAR; PG8_SCHED;
;             PG8_LDB(B0, 1, 0); PG8_LDB(B1, 1, 1); PG8_SCHED; PG8_LDA(At, 1, 0); PG8_STAGE(PG8_SA(0, 1), a2 + hstepA, voffA);
;             PG8_WAIT_V(8); PG8_WAIT_L(0); PG8_BAR; PG8_MMA(0, 0, At, B0); PG8_MMA(0, 1, At, B1); PG8_BAR; PG8_SCHED;
	s_waitcnt lgkmcnt(0)
	v_mfma_f32_16x16x32_bf16 v[60:63], v[142:145], v[182:185], 0
	v_mfma_f32_16x16x32_bf16 v[56:59], v[158:161], v[182:185], 0
	v_mfma_f32_16x16x32_bf16 v[48:51], v[142:145], v[198:201], 0
	v_mfma_f32_16x16x32_bf16 v[40:43], v[158:161], v[198:201], 0
	v_mfma_f32_16x16x32_bf16 v[32:35], v[142:145], v[206:209], 0
	v_mfma_f32_16x16x32_bf16 v[24:27], v[158:161], v[206:209], 0
	v_mfma_f32_16x16x32_bf16 v[16:19], v[142:145], v[214:217], 0
	v_mfma_f32_16x16x32_bf16 v[8:11], v[158:161], v[214:217], 0
	v_mfma_f32_16x16x32_bf16 v[60:63], v[154:157], v[190:193], v[60:63]
	v_mfma_f32_16x16x32_bf16 v[56:59], v[162:165], v[190:193], v[56:59]
	v_mfma_f32_16x16x32_bf16 v[48:51], v[154:157], v[202:205], v[48:51]
	v_mfma_f32_16x16x32_bf16 v[40:43], v[162:165], v[202:205], v[40:43]
	v_mfma_f32_16x16x32_bf16 v[32:35], v[154:157], v[210:213], v[32:35]
	v_mfma_f32_16x16x32_bf16 v[24:27], v[162:165], v[210:213], v[24:27]
	v_mfma_f32_16x16x32_bf16 v[16:19], v[154:157], v[218:221], v[16:19]
	v_mfma_f32_16x16x32_bf16 v[8:11], v[162:165], v[218:221], v[8:11]
	v_mfma_f32_16x16x32_bf16 v[52:55], v[166:169], v[182:185], 0
	v_mfma_f32_16x16x32_bf16 v[44:47], v[174:177], v[182:185], 0
	v_mfma_f32_16x16x32_bf16 v[36:39], v[166:169], v[198:201], 0
	v_mfma_f32_16x16x32_bf16 v[28:31], v[174:177], v[198:201], 0
	v_mfma_f32_16x16x32_bf16 v[20:23], v[166:169], v[206:209], 0
	v_mfma_f32_16x16x32_bf16 v[12:15], v[174:177], v[206:209], 0
	v_mfma_f32_16x16x32_bf16 v[4:7], v[166:169], v[214:217], 0
	v_mfma_f32_16x16x32_bf16 v[0:3], v[174:177], v[214:217], 0
	v_mfma_f32_16x16x32_bf16 v[52:55], v[170:173], v[190:193], v[52:55]
	v_mfma_f32_16x16x32_bf16 v[44:47], v[178:181], v[190:193], v[44:47]
	v_mfma_f32_16x16x32_bf16 v[36:39], v[170:173], v[202:205], v[36:39]
	v_mfma_f32_16x16x32_bf16 v[28:31], v[178:181], v[202:205], v[28:31]
	v_mfma_f32_16x16x32_bf16 v[20:23], v[170:173], v[210:213], v[20:23]
	v_mfma_f32_16x16x32_bf16 v[12:15], v[178:181], v[210:213], v[12:15]
	v_mfma_f32_16x16x32_bf16 v[4:7], v[170:173], v[218:221], v[4:7]
	v_mfma_f32_16x16x32_bf16 v[0:3], v[178:181], v[218:221], v[0:3]
	s_barrier
	s_add_i32 s47, 0, 0x18000
	s_add_i32 s48, 0, 0x1c000
	v_add_u32_e32 v162, s47, v149
	v_add_u32_e32 v178, s48, v149
	ds_read_b128 v[142:145], v162
	ds_read_b128 v[154:157], v162 offset:1024
	ds_read_b128 v[158:161], v162 offset:2048
	ds_read_b128 v[162:165], v162 offset:3072
	ds_read_b128 v[166:169], v178
	ds_read_b128 v[170:173], v178 offset:1024
	ds_read_b128 v[174:177], v178 offset:2048
	ds_read_b128 v[178:181], v178 offset:3072
	s_add_u32 s20, s20, 0x40000
	s_addc_u32 s21, s21, 0
	s_mov_b32 m0, s27
	v_lshl_add_u64 v[224:225], s[20:21], 0, v[128:129]
	ds_read_b128 v[182:185], v153 offset:32768
	ds_read_b128 v[190:193], v153 offset:33792
	ds_read_b128 v[198:201], v153 offset:34816
	ds_read_b128 v[202:205], v153 offset:35840
	ds_read_b128 v[206:209], v153 offset:36864
	ds_read_b128 v[210:213], v153 offset:37888
	ds_read_b128 v[214:217], v153 offset:38912
	ds_read_b128 v[218:221], v153 offset:39936
	global_load_lds_dwordx4 v[224:225], off
	v_lshl_add_u64 v[224:225], s[20:21], 0, v[132:133]
	s_mov_b32 m0, s28
	s_nop 0
	global_load_lds_dwordx4 v[224:225], off
	s_waitcnt vmcnt(8)
	s_waitcnt lgkmcnt(0)
	s_barrier
	s_waitcnt lgkmcnt(0)
	v_mfma_f32_16x16x32_bf16 v[124:127], v[142:145], v[182:185], v[124:127]
	v_mfma_f32_16x16x32_bf16 v[120:123], v[158:161], v[182:185], v[120:123]
	v_mfma_f32_16x16x32_bf16 v[116:119], v[142:145], v[198:201], v[116:119]
	v_mfma_f32_16x16x32_bf16 v[112:115], v[158:161], v[198:201], v[112:115]
	v_mfma_f32_16x16x32_bf16 v[96:99], v[142:145], v[206:209], v[96:99]
	v_mfma_f32_16x16x32_bf16 v[88:91], v[158:161], v[206:209], v[88:91]
	v_mfma_f32_16x16x32_bf16 v[80:83], v[142:145], v[214:217], v[80:83]
	v_mfma_f32_16x16x32_bf16 v[72:75], v[158:161], v[214:217], v[72:75]
	v_mfma_f32_16x16x32_bf16 v[124:127], v[154:157], v[190:193], v[124:127]
	v_mfma_f32_16x16x32_bf16 v[120:123], v[162:165], v[190:193], v[120:123]
	v_mfma_f32_16x16x32_bf16 v[116:119], v[154:157], v[202:205], v[116:119]
	v_mfma_f32_16x16x32_bf16 v[112:115], v[162:165], v[202:205], v[112:115]
	v_mfma_f32_16x16x32_bf16 v[96:99], v[154:157], v[210:213], v[96:99]
	v_mfma_f32_16x16x32_bf16 v[88:91], v[162:165], v[210:213], v[88:91]
	v_mfma_f32_16x16x32_bf16 v[80:83], v[154:157], v[218:221], v[80:83]
	v_mfma_f32_16x16x32_bf16 v[72:75], v[162:165], v[218:221], v[72:75]
	v_mfma_f32_16x16x32_bf16 v[108:111], v[166:169], v[182:185], v[108:111]
	v_mfma_f32_16x16x32_bf16 v[104:107], v[174:177], v[182:185], v[104:107]
	v_mfma_f32_16x16x32_bf16 v[100:103], v[166:169], v[198:201], v[100:103]
	v_mfma_f32_16x16x32_bf16 v[92:95], v[174:177], v[198:201], v[92:95]
	v_mfma_f32_16x16x32_bf16 v[84:87], v[166:169], v[206:209], v[84:87]
	v_mfma_f32_16x16x32_bf16 v[76:79], v[174:177], v[206:209], v[76:79]
	v_mfma_f32_16x16x32_bf16 v[68:71], v[166:169], v[214:217], v[68:71]
	v_mfma_f32_16x16x32_bf16 v[64:67], v[174:177], v[214:217], v[64:67]
	v_mfma_f32_16x16x32_bf16 v[108:111], v[170:173], v[190:193], v[108:111]
	v_mfma_f32_16x16x32_bf16 v[104:107], v[178:181], v[190:193], v[104:107]
	v_mfma_f32_16x16x32_bf16 v[100:103], v[170:173], v[202:205], v[100:103]
	v_mfma_f32_16x16x32_bf16 v[92:95], v[178:181], v[202:205], v[92:95]
	v_mfma_f32_16x16x32_bf16 v[84:87], v[170:173], v[210:213], v[84:87]
	v_mfma_f32_16x16x32_bf16 v[76:79], v[178:181], v[210:213], v[76:79]
	v_mfma_f32_16x16x32_bf16 v[68:71], v[170:173], v[218:221], v[68:71]
	v_mfma_f32_16x16x32_bf16 v[64:67], v[178:181], v[218:221], v[64:67]
	s_barrier
; #define PG8_STAGE(bufoff, gbase, voff) do { _Pragma("unroll") for (int _i = 0; _i < 2; ++_i) \
;         __builtin_amdgcn_global_load_lds((const unsigned*)((const char*)(gbase) + (voff)[_i]), (LAS unsigned*)(lds + (bufoff) + ldsw + _i * 8192), 16, 0, 0); } while (0)
; #define PG8_LDA(dst, b, h) do { _Pragma("unroll") for (int m = 0; m < 4; ++m) _Pragma("unroll") for (int k = 0; k < 2; ++k) dst[m][k] = *(const LAS bf16x8*)(lds + PG8_SA(b, h) + aoff + m * 2048 + k * 1024); } while (0)
; #define PG8_MMA(ai, bj, At, Bt) do { __builtin_amdgcn_s_setprio(1); _Pragma("unroll") for (int m = 0; m < 4; ++m) _Pragma("unroll") for (int n = 0; n < 2; ++n) _Pragma("unroll") for (int k = 0; k < 2; ++k) \
;         acc[ai][bj][m][n] = __builtin_amdgcn_mfma_f32_16x16x32_bf16(Bt[n][k], At[m][k], acc[ai][bj][m][n], 0, 0, 0); __builtin_amdgcn_s_setprio(0); } while (0)
; #define PG8_WAIT_V(n) asm volatile("s_waitcnt vmcnt(" #n ")" ::: "memory")
; #define PG8_WAIT_L(n) asm volatile("s_waitcnt lgkmcnt(" #n ")" ::: "memory")
; #define PG8_BAR __builtin_amdgcn_s_barrier()
; #define PG8_SCHED __builtin_amdgcn_sched_barrier(0)
; template <class Epi>
; __device__ __forceinline__ void gemm_phase(LAS unsigned char* lds, const Gemm g, const StaticOrder& S, const Epi& E) {
;     ...
;             PG8_LDA(At, 1, 1); PG8_STAGE(PG8_SB(1, 0), b3, voffB); PG8_STAGE(PG8_SB(1, 1), b3 + hstepB, voffB); PG8_STAGE(PG8_SA(1, 0), a3, voffA);
;             PG8_WAIT_V(8); PG8_WAIT_L(0); PG8_BAR; PG8_MMA(1, 0, At, B0); PG8_MMA(1, 1, At, B1); PG8_BAR; PG8_SCHED;
;         }
	s_add_i32 s20, s47, s22
	v_lshl_add_u64 v[146:147], v[146:147], 0, s[8:9]
	s_mov_b32 m0, s20
	ds_read_b128 v[182:185], v153 offset:49152
	ds_read_b128 v[190:193], v153 offset:50176
	ds_read_b128 v[198:201], v153 offset:51200
	ds_read_b128 v[202:205], v153 offset:52224
	ds_read_b128 v[206:209], v153 offset:53248
	ds_read_b128 v[210:213], v153 offset:54272
	ds_read_b128 v[214:217], v153 offset:55296
	ds_read_b128 v[218:221], v153 offset:56320
	global_load_lds_dwordx4 v[146:147], off
	s_add_i32 m0, s20, 0x2000
	s_add_u32 s2, s2, 0x20080
	v_lshl_add_u64 v[146:147], v[186:187], 0, s[8:9]
	s_addc_u32 s3, s3, 0
	s_add_i32 s20, s48, s22
	global_load_lds_dwordx4 v[146:147], off
	v_lshl_add_u64 v[146:147], s[2:3], 0, v[130:131]
	s_mov_b32 m0, s20
	s_nop 0
	global_load_lds_dwordx4 v[146:147], off
	v_lshl_add_u64 v[146:147], s[2:3], 0, v[134:135]
	s_add_i32 m0, s20, 0x2000
	s_nop 0
	global_load_lds_dwordx4 v[146:147], off
	v_lshl_add_u64 v[146:147], v[194:195], 0, s[8:9]
	s_mov_b32 m0, s30
	s_nop 0
	global_load_lds_dwordx4 v[146:147], off
	v_lshl_add_u64 v[146:147], v[222:223], 0, s[8:9]
	s_mov_b32 m0, s31
	s_nop 0
	global_load_lds_dwordx4 v[146:147], off
	s_waitcnt vmcnt(8)
	s_waitcnt lgkmcnt(0)
	s_barrier
	s_waitcnt lgkmcnt(0)
	v_mfma_f32_16x16x32_bf16 v[60:63], v[142:145], v[182:185], v[60:63]
	v_mfma_f32_16x16x32_bf16 v[56:59], v[158:161], v[182:185], v[56:59]
	v_mfma_f32_16x16x32_bf16 v[48:51], v[142:145], v[198:201], v[48:51]
	v_mfma_f32_16x16x32_bf16 v[40:43], v[158:161], v[198:201], v[40:43]
	v_mfma_f32_16x16x32_bf16 v[32:35], v[142:145], v[206:209], v[32:35]
	v_mfma_f32_16x16x32_bf16 v[24:27], v[158:161], v[206:209], v[24:27]
	v_mfma_f32_16x16x32_bf16 v[16:19], v[142:145], v[214:217], v[16:19]
	v_mfma_f32_16x16x32_bf16 v[8:11], v[158:161], v[214:217], v[8:11]
	v_mfma_f32_16x16x32_bf16 v[60:63], v[154:157], v[190:193], v[60:63]
	v_mfma_f32_16x16x32_bf16 v[56:59], v[162:165], v[190:193], v[56:59]
	v_mfma_f32_16x16x32_bf16 v[48:51], v[154:157], v[202:205], v[48:51]
	v_mfma_f32_16x16x32_bf16 v[40:43], v[162:165], v[202:205], v[40:43]
	v_mfma_f32_16x16x32_bf16 v[32:35], v[154:157], v[210:213], v[32:35]
	v_mfma_f32_16x16x32_bf16 v[24:27], v[162:165], v[210:213], v[24:27]
	v_mfma_f32_16x16x32_bf16 v[16:19], v[154:157], v[218:221], v[16:19]
	v_mfma_f32_16x16x32_bf16 v[8:11], v[162:165], v[218:221], v[8:11]
	v_mfma_f32_16x16x32_bf16 v[52:55], v[166:169], v[182:185], v[52:55]
	v_mfma_f32_16x16x32_bf16 v[44:47], v[174:177], v[182:185], v[44:47]
	v_mfma_f32_16x16x32_bf16 v[36:39], v[166:169], v[198:201], v[36:39]
	v_mfma_f32_16x16x32_bf16 v[28:31], v[174:177], v[198:201], v[28:31]
	v_mfma_f32_16x16x32_bf16 v[20:23], v[166:169], v[206:209], v[20:23]
	v_mfma_f32_16x16x32_bf16 v[12:15], v[174:177], v[206:209], v[12:15]
	v_mfma_f32_16x16x32_bf16 v[4:7], v[166:169], v[214:217], v[4:7]
	v_mfma_f32_16x16x32_bf16 v[0:3], v[174:177], v[214:217], v[0:3]
	v_mfma_f32_16x16x32_bf16 v[52:55], v[170:173], v[190:193], v[52:55]
	v_mfma_f32_16x16x32_bf16 v[44:47], v[178:181], v[190:193], v[44:47]
	v_mfma_f32_16x16x32_bf16 v[36:39], v[170:173], v[202:205], v[36:39]
	v_mfma_f32_16x16x32_bf16 v[28:31], v[178:181], v[202:205], v[28:31]
	v_mfma_f32_16x16x32_bf16 v[20:23], v[170:173], v[210:213], v[20:23]
	v_mfma_f32_16x16x32_bf16 v[12:15], v[178:181], v[210:213], v[12:15]
	v_mfma_f32_16x16x32_bf16 v[4:7], v[170:173], v[218:221], v[4:7]
	v_mfma_f32_16x16x32_bf16 v[0:3], v[178:181], v[218:221], v[0:3]
	s_barrier
	s_add_i32 s46, s46, 2
	s_add_u32 s18, s18, 0x100
	s_addc_u32 s19, s19, 0
	s_add_u32 s44, s44, 0x100
	s_addc_u32 s45, s45, 0
	s_cmp_gt_u32 s46, 5
	s_cbranch_scc0 .LBB0_697

; #define PG8_STAGE(bufoff, gbase, voff) do { _Pragma("unroll") for (int _i = 0; _i < 2; ++_i) \
;         __builtin_amdgcn_global_load_lds((const unsigned*)((const char*)(gbase) + (voff)[_i]), (LAS unsigned*)(lds + (bufoff) + ldsw + _i * 8192), 16, 0, 0); } while (0)
; #define PG8_WAIT_V(n) asm volatile("s_waitcnt vmcnt(" #n ")" ::: "memory")
; #define PG8_BAR __builtin_amdgcn_s_barrier()
; template <class Epi>
; __device__ __forceinline__ void gemm_phase(LAS unsigned char* lds, const Gemm g, const StaticOrder& S, const Epi& E) {
;     ...
;     const size_t aslab = g.aslab ? g.aslab : 32 * tstepA;
;     const char* cA = (const char*)g.A + (size_t)(cur.pm >> 5) * aslab + (size_t)(cur.pm & 31) * tstepA; const char* cB = (const char*)g.Bt + (size_t)cur.pn * tstepB;
;     PG8_STAGE(PG8_SB(0, 0), cB, voffB); PG8_STAGE(PG8_SB(0, 1), cB + hstepB, voffB); PG8_STAGE(PG8_SA(0, 0), cA, voffA); PG8_STAGE(PG8_SA(0, 1), cA + hstepA, voffA);
;     if (wr == 1) PG8_BAR;
;     PG8_WAIT_V(2); PG8_BAR;
;     PG8_STAGE(PG8_SB(1, 0), cB + kstep, voffB); PG8_STAGE(PG8_SA(1, 0), cA + kstep, voffA); PG8_STAGE(PG8_SB(1, 1), cB + hstepB + kstep, voffB);
;     PG8_WAIT_V(6); PG8_BAR;
.LBB0_711:
	s_add_u32 s8, s72, 0xc001a00
	s_addc_u32 s9, s73, 0
	s_lshl_b32 s10, s10, 5
	s_and_b32 s17, s10, 0x60
	s_mov_b64 s[10:11], 0x80
	s_add_i32 m0, s27, 0x18000
	v_lshl_add_u64 v[6:7], v[6:7], 0, s[10:11]
	s_lshl_b32 s16, s13, 13
	s_lshl_b32 s18, s17, 7
	global_load_lds_dwordx4 v[6:7], off
	v_lshl_add_u64 v[4:5], v[4:5], 0, s[10:11]
	s_add_i32 m0, s27, 0x1a000
	s_add_i32 s33, s27, 0x8000
	s_add_i32 s34, s27, 0xa000
	global_load_lds_dwordx4 v[4:5], off
	v_lshl_add_u64 v[0:1], v[0:1], 0, s[10:11]
	s_mov_b32 m0, s33
	s_add_u32 s14, s2, 0x20080
	global_load_lds_dwordx4 v[0:1], off
	v_lshl_add_u64 v[0:1], v[2:3], 0, s[10:11]
	s_mov_b32 m0, s34
	s_addc_u32 s15, s3, 0
	global_load_lds_dwordx4 v[0:1], off
	s_add_i32 m0, s27, 0x1c000
	v_lshl_add_u64 v[0:1], s[14:15], 0, v[146:147]
	global_load_lds_dwordx4 v[0:1], off
	v_lshl_add_u64 v[0:1], s[14:15], 0, v[150:151]
	s_add_i32 m0, s27, 0x1e000
	s_cmpk_lt_u32 s12, 0x100
	global_load_lds_dwordx4 v[0:1], off
	s_waitcnt vmcnt(8)
	s_barrier
	v_lshrrev_b32_e32 v1, 1, v8
	v_and_b32_e32 v1, 24, v1
	v_and_b32_e32 v0, 15, v8
	v_lshlrev_b32_e32 v2, 1, v1
	v_lshl_or_b32 v164, s13, 6, v0
	v_lshl_or_b32 v0, v0, 6, v2
	v_lshlrev_b32_e32 v2, 2, v8
	v_and_b32_e32 v2, 32, v2
	v_bitop3_b32 v3, v0, s16, v2 bitop3:0xde
	v_bitop3_b32 v165, v0, s18, v2 bitop3:0xde
	v_lshlrev_b32_e32 v0, 14, v9
	v_and_b32_e32 v0, 0xffff8000, v0
	v_or_b32_e32 v166, s17, v1
	v_lshl_add_u32 v0, v10, 11, v0
	v_and_b32_e32 v1, 1, v9
	v_lshl_or_b32 v0, v1, 6, v0
	v_lshl_add_u32 v152, v11, 1, v0
	v_lshlrev_b32_e32 v0, 14, v12
	s_sext_i32_i8 s43, s4
	s_cselect_b64 s[12:13], -1, 0
	s_ashr_i32 s35, s74, 31
	v_readlane_b32 s4, v235, 0
	v_and_b32_e32 v0, 0xffff8000, v0
	s_waitcnt vmcnt(6)
	s_sub_u32 s4, 0x400, s4
	v_lshl_add_u32 v0, v13, 11, v0
	v_and_b32_e32 v1, 1, v12
	s_subb_u32 s5, 0, s5
	v_lshl_or_b32 v0, v1, 6, v0
	s_add_i32 s37, 0, 0x10000
	s_add_i32 s38, 0, 0x14000
	s_mov_b32 s36, s74
	v_mov_b32_e32 v153, v147
	v_lshl_add_u32 v154, v14, 1, v0
	v_mov_b32_e32 v155, v147
	v_mov_b64_e32 v[156:157], s[4:5]
	v_add_u32_e32 v167, s37, v165
	v_add_u32_e32 v168, s38, v165
	v_add_u32_e32 v169, 0, v3
	s_movk_i32 s39, 0x1100
	s_movk_i32 s40, 0x2200
	s_barrier
	s_branch .LBB0_714

; #define PG8_STAGE(bufoff, gbase, voff) do { _Pragma("unroll") for (int _i = 0; _i < 2; ++_i) \
;         __builtin_amdgcn_global_load_lds((const unsigned*)((const char*)(gbase) + (voff)[_i]), (LAS unsigned*)(lds + (bufoff) + ldsw + _i * 8192), 16, 0, 0); } while (0)
; #define PG8_LDA(dst, b, h) do { _Pragma("unroll") for (int m = 0; m < 4; ++m) _Pragma("unroll") for (int k = 0; k < 2; ++k) dst[m][k] = *(const LAS bf16x8*)(lds + PG8_SA(b, h) + aoff + m * 2048 + k * 1024); } while (0)
; #define PG8_LDB(dst, b, h) do { _Pragma("unroll") for (int n = 0; n < 2; ++n) _Pragma("unroll") for (int k = 0; k < 2; ++k) dst[n][k] = *(const LAS bf16x8*)(lds + PG8_SB(b, h) + boff + n * 2048 + k * 1024); } while (0)
; #define PG8_MMA(ai, bj, At, Bt) do { __builtin_amdgcn_s_setprio(1); _Pragma("unroll") for (int m = 0; m < 4; ++m) _Pragma("unroll") for (int n = 0; n < 2; ++n) _Pragma("unroll") for (int k = 0; k < 2; ++k) \
;         acc[ai][bj][m][n] = __builtin_amdgcn_mfma_f32_16x16x32_bf16(Bt[n][k], At[m][k], acc[ai][bj][m][n], 0, 0, 0); __builtin_amdgcn_s_setprio(0); } while (0)
; template <class Epi>
; __device__ __forceinline__ void gemm_phase(LAS unsigned char* lds, const Gemm g, const StaticOrder& S, const Epi& E) {
;     ...
;         const bool has_next = S.next(ui + 1, nxt);
;         const char* nA = has_next ? (const char*)g.A + (size_t)(nxt.pm >> 5) * aslab + (size_t)(nxt.pm & 31) * tstepA : cA; const char* nB = has_next ? (const char*)g.Bt + (size_t)nxt.pn * tstepB : cB;
;         for (int t = 0; t < nt; t += 2) {
;             const bool last = (t == nt - 2);
;             const char* a1 = cA + (size_t)(t + 1) * kstep;
;             const char* a2 = last ? nA : cA + (size_t)(t + 2) * kstep; const char* b2 = last ? nB : cB + (size_t)(t + 2) * kstep;
;             const char* a3 = a2 + kstep; const char* b3 = b2 + kstep;
;             PG8_LDB(B0, 0, 0); PG8_LDB(B1, 0, 1); PG8_SCHED; PG8_LDA(At, 0, 0); PG8_STAGE(PG8_SA(1, 1), a1 + hstepA, voffA);
;             PG8_WAIT_V(8); PG8_WAIT_L(0); PG8_BAR; PG8_MMA(0, 0, At, B0); PG8_MMA(0, 1, At, B1); PG8_BAR; PG8_SCHED;
;             PG8_LDA(At, 0, 1); PG8_STAGE(PG8_SB(0, 0), b2, voffB); PG8_STAGE(PG8_SB(0, 1), b2 + hstepB, voffB); PG8_STAGE(PG8_SA(0, 0), a2, voffA);
;             PG8_WAIT_V(8); PG8_WAIT_L(0); PG8_BAR; PG8_MMA(1, 0, At, B0); PG8_MMA(1, 1, At, B1); PG8_BAR; PG8_SCHED;
.LBB0_720:
	s_ashr_i32 s16, s41, 5
	s_ashr_i32 s17, s16, 31
	s_lshl_b64 s[16:17], s[16:17], 24
	s_add_u32 s15, s24, s16
	s_addc_u32 s17, s25, s17
	s_lshl_b32 s16, s41, 19
	s_and_b32 s16, s16, 0xf80000
	s_add_u32 s16, s15, s16
	s_addc_u32 s17, s17, 0
	s_and_b64 s[18:19], s[4:5], exec
	s_cselect_b32 s44, s17, s21
	s_cselect_b32 s45, s16, s20
	s_ashr_i32 s15, s14, 31
	s_lshl_b64 s[18:19], s[14:15], 18
	v_readlane_b32 s22, v235, 27
	v_readlane_b32 s23, v235, 28
	s_add_u32 s18, s22, s18
	s_addc_u32 s19, s23, s19
	s_and_b64 s[22:23], s[4:5], exec
	s_cselect_b32 s15, s19, s3
	s_cselect_b32 s46, s18, s2
	s_add_u32 s20, s20, 0x40080
	s_addc_u32 s21, s21, 0
	s_add_u32 s47, s2, 0x100
	s_addc_u32 s48, s3, 0
	s_mov_b32 s49, -2
	ds_read_b128 v[128:131], v167
	ds_read_b128 v[132:135], v167 offset:1024
	ds_read_b128 v[136:139], v167 offset:2048
	ds_read_b128 v[140:143], v167 offset:3072
	ds_read_b128 v[158:161], v168
	ds_read_b128 v[170:173], v168 offset:1024
	ds_read_b128 v[174:177], v168 offset:2048
	ds_read_b128 v[178:181], v168 offset:3072
	s_add_u32 s2, s20, 0xfffc0080
	s_addc_u32 s3, s21, -1
	s_cmp_eq_u32 s49, 4
	s_cselect_b32 s23, s44, s3
	s_cselect_b32 s22, s45, s2
	s_cselect_b32 s3, s15, s48
	s_cselect_b32 s2, s46, s47
	v_lshl_add_u64 v[162:163], s[20:21], 0, v[152:153]
	s_add_i32 m0, s27, 0xc000
	ds_read_b128 v[182:185], v169
	ds_read_b128 v[190:193], v169 offset:1024
	ds_read_b128 v[198:201], v169 offset:2048
	ds_read_b128 v[202:205], v169 offset:3072
	ds_read_b128 v[206:209], v169 offset:4096
	ds_read_b128 v[210:213], v169 offset:5120
	ds_read_b128 v[214:217], v169 offset:6144
	ds_read_b128 v[218:221], v169 offset:7168
	global_load_lds_dwordx4 v[162:163], off
	v_lshl_add_u64 v[162:163], s[20:21], 0, v[154:155]
	s_add_i32 m0, s27, 0xe000
	s_nop 0
	global_load_lds_dwordx4 v[162:163], off
	s_waitcnt vmcnt(8)
	s_waitcnt lgkmcnt(0)
	s_barrier
	s_waitcnt lgkmcnt(0)
	v_mfma_f32_16x16x32_bf16 v[124:127], v[128:131], v[182:185], 0
	v_mfma_f32_16x16x32_bf16 v[120:123], v[136:139], v[182:185], 0
	v_mfma_f32_16x16x32_bf16 v[112:115], v[128:131], v[198:201], 0
	v_mfma_f32_16x16x32_bf16 v[104:107], v[136:139], v[198:201], 0
	v_mfma_f32_16x16x32_bf16 v[96:99], v[128:131], v[206:209], 0
	v_mfma_f32_16x16x32_bf16 v[88:91], v[136:139], v[206:209], 0
	v_mfma_f32_16x16x32_bf16 v[80:83], v[128:131], v[214:217], 0
	v_mfma_f32_16x16x32_bf16 v[72:75], v[136:139], v[214:217], 0
	v_mfma_f32_16x16x32_bf16 v[124:127], v[132:135], v[190:193], v[124:127]
	v_mfma_f32_16x16x32_bf16 v[120:123], v[140:143], v[190:193], v[120:123]
	v_mfma_f32_16x16x32_bf16 v[112:115], v[132:135], v[202:205], v[112:115]
	v_mfma_f32_16x16x32_bf16 v[104:107], v[140:143], v[202:205], v[104:107]
	v_mfma_f32_16x16x32_bf16 v[96:99], v[132:135], v[210:213], v[96:99]
	v_mfma_f32_16x16x32_bf16 v[88:91], v[140:143], v[210:213], v[88:91]
	v_mfma_f32_16x16x32_bf16 v[80:83], v[132:135], v[218:221], v[80:83]
	v_mfma_f32_16x16x32_bf16 v[72:75], v[140:143], v[218:221], v[72:75]
	v_mfma_f32_16x16x32_bf16 v[116:119], v[158:161], v[182:185], 0
	v_mfma_f32_16x16x32_bf16 v[108:111], v[174:177], v[182:185], 0
	v_mfma_f32_16x16x32_bf16 v[100:103], v[158:161], v[198:201], 0
	v_mfma_f32_16x16x32_bf16 v[92:95], v[174:177], v[198:201], 0
	v_mfma_f32_16x16x32_bf16 v[84:87], v[158:161], v[206:209], 0
	v_mfma_f32_16x16x32_bf16 v[76:79], v[174:177], v[206:209], 0
	v_mfma_f32_16x16x32_bf16 v[68:71], v[158:161], v[214:217], 0
	v_mfma_f32_16x16x32_bf16 v[64:67], v[174:177], v[214:217], 0
	v_mfma_f32_16x16x32_bf16 v[116:119], v[170:173], v[190:193], v[116:119]
	v_mfma_f32_16x16x32_bf16 v[108:111], v[178:181], v[190:193], v[108:111]
	v_mfma_f32_16x16x32_bf16 v[100:103], v[170:173], v[202:205], v[100:103]
	v_mfma_f32_16x16x32_bf16 v[92:95], v[178:181], v[202:205], v[92:95]
	v_mfma_f32_16x16x32_bf16 v[84:87], v[170:173], v[210:213], v[84:87]
	v_mfma_f32_16x16x32_bf16 v[76:79], v[178:181], v[210:213], v[76:79]
	v_mfma_f32_16x16x32_bf16 v[68:71], v[170:173], v[218:221], v[68:71]
	v_mfma_f32_16x16x32_bf16 v[64:67], v[178:181], v[218:221], v[64:67]
	s_barrier
	s_add_i32 s50, s37, s26
	v_lshl_add_u64 v[162:163], s[2:3], 0, v[146:147]
	s_mov_b32 m0, s50
	ds_read_b128 v[182:185], v169 offset:16384
	ds_read_b128 v[190:193], v169 offset:17408
	ds_read_b128 v[198:201], v169 offset:18432
	ds_read_b128 v[202:205], v169 offset:19456
	ds_read_b128 v[206:209], v169 offset:20480
	ds_read_b128 v[210:213], v169 offset:21504
	ds_read_b128 v[214:217], v169 offset:22528
	ds_read_b128 v[218:221], v169 offset:23552
	global_load_lds_dwordx4 v[162:163], off
	s_add_i32 m0, s50, 0x2000
	s_add_u32 s50, s2, 0x20000
	v_lshl_add_u64 v[186:187], s[2:3], 0, v[150:151]
	s_addc_u32 s51, s3, 0
	s_add_i32 s52, s38, s26
	global_load_lds_dwordx4 v[186:187], off
	v_lshl_add_u64 v[194:195], s[50:51], 0, v[146:147]
	s_mov_b32 m0, s52
	v_lshl_add_u64 v[222:223], s[22:23], 0, v[148:149]
	global_load_lds_dwordx4 v[194:195], off
	v_lshl_add_u64 v[194:195], s[50:51], 0, v[150:151]
	s_add_i32 m0, s52, 0x2000
	s_nop 0
	global_load_lds_dwordx4 v[194:195], off
	v_lshl_add_u64 v[194:195], s[22:23], 0, v[144:145]
	s_mov_b32 m0, s27
	s_nop 0
	global_load_lds_dwordx4 v[194:195], off
	s_mov_b32 m0, s28
	s_nop 0
	global_load_lds_dwordx4 v[222:223], off
	s_waitcnt vmcnt(8)
	s_waitcnt lgkmcnt(0)
	s_barrier
; #define PG8_STAGE(bufoff, gbase, voff) do { _Pragma("unroll") for (int _i = 0; _i < 2; ++_i) \
;         __builtin_amdgcn_global_load_lds((const unsigned*)((const char*)(gbase) + (voff)[_i]), (LAS unsigned*)(lds + (bufoff) + ldsw + _i * 8192), 16, 0, 0); } while (0)
; #define PG8_LDA(dst, b, h) do { _Pragma("unroll") for (int m = 0; m < 4; ++m) _Pragma("unroll") for (int k = 0; k < 2; ++k) dst[m][k] = *(const LAS bf16x8*)(lds + PG8_SA(b, h) + aoff + m * 2048 + k * 1024); } while (0)
; #define PG8_LDB(dst, b, h) do { _Pragma("unroll") for (int n = 0; n < 2; ++n) _Pragma("unroll") for (int k = 0; k < 2; ++k) dst[n][k] = *(const LAS bf16x8*)(lds + PG8_SB(b, h) + boff + n * 2048 + k * 1024); } while (0)
; #define PG8_MMA(ai, bj, At, Bt) do { __builtin_amdgcn_s_setprio(1); _Pragma("unroll") for (int m = 0; m < 4; ++m) _Pragma("unroll") for (int n = 0; n < 2; ++n) _Pragma("unroll") for (int k = 0; k < 2; ++k) \
;         acc[ai][bj][m][n] = __builtin_amdgcn_mfma_f32_16x16x32_bf16(Bt[n][k], At[m][k], acc[ai][bj][m][n], 0, 0, 0); __builtin_amdgcn_s_setprio(0); } while (0)
; #define PG8_WAIT_V(n) asm volatile("s_waitcnt vmcnt(" #n ")" ::: "memory")
; #define PG8_WAIT_L(n) asm volatile("s_waitcnt lgkmcnt(" #n ")" ::: "memory")
; #define PG8_BAR __builtin_amdgcn_s_barrier()
; #define PG8_SCHED __builtin_amdgcn_sched_barrier(0)
; template <class Epi>
; __device__ __forceinline__ void gemm_phase(LAS unsigned char* lds, const Gemm g, const StaticOrder& S, const Epi& E) {
;     ...
;             PG8_WAIT_V(8); PG8_WAIT_L(0); PG8_BAR; PG8_MMA(1, 0, At, B0); PG8_MMA(1, 1, At, B1); PG8_BAR; PG8_SCHED;
;             PG8_LDB(B0, 1, 0); PG8_LDB(B1, 1, 1); PG8_SCHED; PG8_LDA(At, 1, 0); PG8_STAGE(PG8_SA(0, 1), a2 + hstepA, voffA);
;             PG8_WAIT_V(8); PG8_WAIT_L(0); PG8_BAR; PG8_MMA(0, 0, At, B0); PG8_MMA(0, 1, At, B1); PG8_BAR; PG8_SCHED;
	s_waitcnt lgkmcnt(0)
	v_mfma_f32_16x16x32_bf16 v[60:63], v[128:131], v[182:185], 0
	v_mfma_f32_16x16x32_bf16 v[56:59], v[136:139], v[182:185], 0
	v_mfma_f32_16x16x32_bf16 v[48:51], v[128:131], v[198:201], 0
	v_mfma_f32_16x16x32_bf16 v[40:43], v[136:139], v[198:201], 0
	v_mfma_f32_16x16x32_bf16 v[32:35], v[128:131], v[206:209], 0
	v_mfma_f32_16x16x32_bf16 v[24:27], v[136:139], v[206:209], 0
	v_mfma_f32_16x16x32_bf16 v[16:19], v[128:131], v[214:217], 0
	v_mfma_f32_16x16x32_bf16 v[8:11], v[136:139], v[214:217], 0
	v_mfma_f32_16x16x32_bf16 v[60:63], v[132:135], v[190:193], v[60:63]
	v_mfma_f32_16x16x32_bf16 v[56:59], v[140:143], v[190:193], v[56:59]
	v_mfma_f32_16x16x32_bf16 v[48:51], v[132:135], v[202:205], v[48:51]
	v_mfma_f32_16x16x32_bf16 v[40:43], v[140:143], v[202:205], v[40:43]
	v_mfma_f32_16x16x32_bf16 v[32:35], v[132:135], v[210:213], v[32:35]
	v_mfma_f32_16x16x32_bf16 v[24:27], v[140:143], v[210:213], v[24:27]
	v_mfma_f32_16x16x32_bf16 v[16:19], v[132:135], v[218:221], v[16:19]
	v_mfma_f32_16x16x32_bf16 v[8:11], v[140:143], v[218:221], v[8:11]
	v_mfma_f32_16x16x32_bf16 v[52:55], v[158:161], v[182:185], 0
	v_mfma_f32_16x16x32_bf16 v[44:47], v[174:177], v[182:185], 0
	v_mfma_f32_16x16x32_bf16 v[36:39], v[158:161], v[198:201], 0
	v_mfma_f32_16x16x32_bf16 v[28:31], v[174:177], v[198:201], 0
	v_mfma_f32_16x16x32_bf16 v[20:23], v[158:161], v[206:209], 0
	v_mfma_f32_16x16x32_bf16 v[12:15], v[174:177], v[206:209], 0
	v_mfma_f32_16x16x32_bf16 v[4:7], v[158:161], v[214:217], 0
	v_mfma_f32_16x16x32_bf16 v[0:3], v[174:177], v[214:217], 0
	v_mfma_f32_16x16x32_bf16 v[52:55], v[170:173], v[190:193], v[52:55]
	v_mfma_f32_16x16x32_bf16 v[44:47], v[178:181], v[190:193], v[44:47]
	v_mfma_f32_16x16x32_bf16 v[36:39], v[170:173], v[202:205], v[36:39]
	v_mfma_f32_16x16x32_bf16 v[28:31], v[178:181], v[202:205], v[28:31]
	v_mfma_f32_16x16x32_bf16 v[20:23], v[170:173], v[210:213], v[20:23]
	v_mfma_f32_16x16x32_bf16 v[12:15], v[178:181], v[210:213], v[12:15]
	v_mfma_f32_16x16x32_bf16 v[4:7], v[170:173], v[218:221], v[4:7]
	v_mfma_f32_16x16x32_bf16 v[0:3], v[178:181], v[218:221], v[0:3]
	s_barrier
	s_add_i32 s50, 0, 0x18000
	s_add_i32 s51, 0, 0x1c000
	v_add_u32_e32 v140, s50, v165
	v_add_u32_e32 v178, s51, v165
	ds_read_b128 v[128:131], v140
	ds_read_b128 v[132:135], v140 offset:1024
	ds_read_b128 v[136:139], v140 offset:2048
	ds_read_b128 v[140:143], v140 offset:3072
	ds_read_b128 v[158:161], v178
	ds_read_b128 v[170:173], v178 offset:1024
	ds_read_b128 v[174:177], v178 offset:2048
	ds_read_b128 v[178:181], v178 offset:3072
	s_add_u32 s22, s22, 0x40000
	s_addc_u32 s23, s23, 0
	s_mov_b32 m0, s29
	v_lshl_add_u64 v[224:225], s[22:23], 0, v[144:145]
	ds_read_b128 v[182:185], v169 offset:32768
	ds_read_b128 v[190:193], v169 offset:33792
	ds_read_b128 v[198:201], v169 offset:34816
	ds_read_b128 v[202:205], v169 offset:35840
	ds_read_b128 v[206:209], v169 offset:36864
	ds_read_b128 v[210:213], v169 offset:37888
	ds_read_b128 v[214:217], v169 offset:38912
	ds_read_b128 v[218:221], v169 offset:39936
	global_load_lds_dwordx4 v[224:225], off
	v_lshl_add_u64 v[224:225], s[22:23], 0, v[148:149]
	s_mov_b32 m0, s30
	s_nop 0
	global_load_lds_dwordx4 v[224:225], off
	s_waitcnt vmcnt(8)
	s_waitcnt lgkmcnt(0)
	s_barrier
	s_waitcnt lgkmcnt(0)
	v_mfma_f32_16x16x32_bf16 v[124:127], v[128:131], v[182:185], v[124:127]
	v_mfma_f32_16x16x32_bf16 v[120:123], v[136:139], v[182:185], v[120:123]
	v_mfma_f32_16x16x32_bf16 v[112:115], v[128:131], v[198:201], v[112:115]
	v_mfma_f32_16x16x32_bf16 v[104:107], v[136:139], v[198:201], v[104:107]
	v_mfma_f32_16x16x32_bf16 v[96:99], v[128:131], v[206:209], v[96:99]
	v_mfma_f32_16x16x32_bf16 v[88:91], v[136:139], v[206:209], v[88:91]
	v_mfma_f32_16x16x32_bf16 v[80:83], v[128:131], v[214:217], v[80:83]
	v_mfma_f32_16x16x32_bf16 v[72:75], v[136:139], v[214:217], v[72:75]
	v_mfma_f32_16x16x32_bf16 v[124:127], v[132:135], v[190:193], v[124:127]
	v_mfma_f32_16x16x32_bf16 v[120:123], v[140:143], v[190:193], v[120:123]
	v_mfma_f32_16x16x32_bf16 v[112:115], v[132:135], v[202:205], v[112:115]
	v_mfma_f32_16x16x32_bf16 v[104:107], v[140:143], v[202:205], v[104:107]
	v_mfma_f32_16x16x32_bf16 v[96:99], v[132:135], v[210:213], v[96:99]
	v_mfma_f32_16x16x32_bf16 v[88:91], v[140:143], v[210:213], v[88:91]
	v_mfma_f32_16x16x32_bf16 v[80:83], v[132:135], v[218:221], v[80:83]
	v_mfma_f32_16x16x32_bf16 v[72:75], v[140:143], v[218:221], v[72:75]
	v_mfma_f32_16x16x32_bf16 v[116:119], v[158:161], v[182:185], v[116:119]
	v_mfma_f32_16x16x32_bf16 v[108:111], v[174:177], v[182:185], v[108:111]
	v_mfma_f32_16x16x32_bf16 v[100:103], v[158:161], v[198:201], v[100:103]
	v_mfma_f32_16x16x32_bf16 v[92:95], v[174:177], v[198:201], v[92:95]
	v_mfma_f32_16x16x32_bf16 v[84:87], v[158:161], v[206:209], v[84:87]
	v_mfma_f32_16x16x32_bf16 v[76:79], v[174:177], v[206:209], v[76:79]
	v_mfma_f32_16x16x32_bf16 v[68:71], v[158:161], v[214:217], v[68:71]
	v_mfma_f32_16x16x32_bf16 v[64:67], v[174:177], v[214:217], v[64:67]
	v_mfma_f32_16x16x32_bf16 v[116:119], v[170:173], v[190:193], v[116:119]
	v_mfma_f32_16x16x32_bf16 v[108:111], v[178:181], v[190:193], v[108:111]
	v_mfma_f32_16x16x32_bf16 v[100:103], v[170:173], v[202:205], v[100:103]
	v_mfma_f32_16x16x32_bf16 v[92:95], v[178:181], v[202:205], v[92:95]
	v_mfma_f32_16x16x32_bf16 v[84:87], v[170:173], v[210:213], v[84:87]
	v_mfma_f32_16x16x32_bf16 v[76:79], v[178:181], v[210:213], v[76:79]
	v_mfma_f32_16x16x32_bf16 v[68:71], v[170:173], v[218:221], v[68:71]
	v_mfma_f32_16x16x32_bf16 v[64:67], v[178:181], v[218:221], v[64:67]
	s_barrier
; #define PG8_STAGE(bufoff, gbase, voff) do { _Pragma("unroll") for (int _i = 0; _i < 2; ++_i) \
;         __builtin_amdgcn_global_load_lds((const unsigned*)((const char*)(gbase) + (voff)[_i]), (LAS unsigned*)(lds + (bufoff) + ldsw + _i * 8192), 16, 0, 0); } while (0)
; #define PG8_LDA(dst, b, h) do { _Pragma("unroll") for (int m = 0; m < 4; ++m) _Pragma("unroll") for (int k = 0; k < 2; ++k) dst[m][k] = *(const LAS bf16x8*)(lds + PG8_SA(b, h) + aoff + m * 2048 + k * 1024); } while (0)
; #define PG8_MMA(ai, bj, At, Bt) do { __builtin_amdgcn_s_setprio(1); _Pragma("unroll") for (int m = 0; m < 4; ++m) _Pragma("unroll") for (int n = 0; n < 2; ++n) _Pragma("unroll") for (int k = 0; k < 2; ++k) \
;         acc[ai][bj][m][n] = __builtin_amdgcn_mfma_f32_16x16x32_bf16(Bt[n][k], At[m][k], acc[ai][bj][m][n], 0, 0, 0); __builtin_amdgcn_s_setprio(0); } while (0)
; #define PG8_WAIT_V(n) asm volatile("s_waitcnt vmcnt(" #n ")" ::: "memory")
; #define PG8_WAIT_L(n) asm volatile("s_waitcnt lgkmcnt(" #n ")" ::: "memory")
; #define PG8_BAR __builtin_amdgcn_s_barrier()
; #define PG8_SCHED __builtin_amdgcn_sched_barrier(0)
; template <class Epi>
; __device__ __forceinline__ void gemm_phase(LAS unsigned char* lds, const Gemm g, const StaticOrder& S, const Epi& E) {
;     ...
;             PG8_LDA(At, 1, 1); PG8_STAGE(PG8_SB(1, 0), b3, voffB); PG8_STAGE(PG8_SB(1, 1), b3 + hstepB, voffB); PG8_STAGE(PG8_SA(1, 0), a3, voffA);
;             PG8_WAIT_V(8); PG8_WAIT_L(0); PG8_BAR; PG8_MMA(1, 0, At, B0); PG8_MMA(1, 1, At, B1); PG8_BAR; PG8_SCHED;
;         }
	s_add_i32 s22, s50, s26
	v_lshl_add_u64 v[162:163], v[162:163], 0, s[10:11]
	s_mov_b32 m0, s22
	ds_read_b128 v[182:185], v169 offset:49152
	ds_read_b128 v[190:193], v169 offset:50176
	ds_read_b128 v[198:201], v169 offset:51200
	ds_read_b128 v[202:205], v169 offset:52224
	ds_read_b128 v[206:209], v169 offset:53248
	ds_read_b128 v[210:213], v169 offset:54272
	ds_read_b128 v[214:217], v169 offset:55296
	ds_read_b128 v[218:221], v169 offset:56320
	global_load_lds_dwordx4 v[162:163], off
	s_add_i32 m0, s22, 0x2000
	s_add_u32 s2, s2, 0x20080
	v_lshl_add_u64 v[162:163], v[186:187], 0, s[10:11]
	s_addc_u32 s3, s3, 0
	s_add_i32 s22, s51, s26
	global_load_lds_dwordx4 v[162:163], off
	v_lshl_add_u64 v[162:163], s[2:3], 0, v[146:147]
	s_mov_b32 m0, s22
	s_nop 0
	global_load_lds_dwordx4 v[162:163], off
	v_lshl_add_u64 v[162:163], s[2:3], 0, v[150:151]
	s_add_i32 m0, s22, 0x2000
	s_nop 0
	global_load_lds_dwordx4 v[162:163], off
	v_lshl_add_u64 v[162:163], v[194:195], 0, s[10:11]
	s_mov_b32 m0, s33
	s_nop 0
	global_load_lds_dwordx4 v[162:163], off
	v_lshl_add_u64 v[162:163], v[222:223], 0, s[10:11]
	s_mov_b32 m0, s34
	s_nop 0
	global_load_lds_dwordx4 v[162:163], off
	s_waitcnt vmcnt(8)
	s_waitcnt lgkmcnt(0)
	s_barrier
	s_waitcnt lgkmcnt(0)
	v_mfma_f32_16x16x32_bf16 v[60:63], v[128:131], v[182:185], v[60:63]
	v_mfma_f32_16x16x32_bf16 v[56:59], v[136:139], v[182:185], v[56:59]
	v_mfma_f32_16x16x32_bf16 v[48:51], v[128:131], v[198:201], v[48:51]
	v_mfma_f32_16x16x32_bf16 v[40:43], v[136:139], v[198:201], v[40:43]
	v_mfma_f32_16x16x32_bf16 v[32:35], v[128:131], v[206:209], v[32:35]
	v_mfma_f32_16x16x32_bf16 v[24:27], v[136:139], v[206:209], v[24:27]
	v_mfma_f32_16x16x32_bf16 v[16:19], v[128:131], v[214:217], v[16:19]
	v_mfma_f32_16x16x32_bf16 v[8:11], v[136:139], v[214:217], v[8:11]
	v_mfma_f32_16x16x32_bf16 v[60:63], v[132:135], v[190:193], v[60:63]
	v_mfma_f32_16x16x32_bf16 v[56:59], v[140:143], v[190:193], v[56:59]
	v_mfma_f32_16x16x32_bf16 v[48:51], v[132:135], v[202:205], v[48:51]
	v_mfma_f32_16x16x32_bf16 v[40:43], v[140:143], v[202:205], v[40:43]
	v_mfma_f32_16x16x32_bf16 v[32:35], v[132:135], v[210:213], v[32:35]
	v_mfma_f32_16x16x32_bf16 v[24:27], v[140:143], v[210:213], v[24:27]
	v_mfma_f32_16x16x32_bf16 v[16:19], v[132:135], v[218:221], v[16:19]
	v_mfma_f32_16x16x32_bf16 v[8:11], v[140:143], v[218:221], v[8:11]
	v_mfma_f32_16x16x32_bf16 v[52:55], v[158:161], v[182:185], v[52:55]
	v_mfma_f32_16x16x32_bf16 v[44:47], v[174:177], v[182:185], v[44:47]
	v_mfma_f32_16x16x32_bf16 v[36:39], v[158:161], v[198:201], v[36:39]
	v_mfma_f32_16x16x32_bf16 v[28:31], v[174:177], v[198:201], v[28:31]
	v_mfma_f32_16x16x32_bf16 v[20:23], v[158:161], v[206:209], v[20:23]
	v_mfma_f32_16x16x32_bf16 v[12:15], v[174:177], v[206:209], v[12:15]
	v_mfma_f32_16x16x32_bf16 v[4:7], v[158:161], v[214:217], v[4:7]
	v_mfma_f32_16x16x32_bf16 v[0:3], v[174:177], v[214:217], v[0:3]
	v_mfma_f32_16x16x32_bf16 v[52:55], v[170:173], v[190:193], v[52:55]
	v_mfma_f32_16x16x32_bf16 v[44:47], v[178:181], v[190:193], v[44:47]
	v_mfma_f32_16x16x32_bf16 v[36:39], v[170:173], v[202:205], v[36:39]
	v_mfma_f32_16x16x32_bf16 v[28:31], v[178:181], v[202:205], v[28:31]
	v_mfma_f32_16x16x32_bf16 v[20:23], v[170:173], v[210:213], v[20:23]
	v_mfma_f32_16x16x32_bf16 v[12:15], v[178:181], v[210:213], v[12:15]
	v_mfma_f32_16x16x32_bf16 v[4:7], v[170:173], v[218:221], v[4:7]
	v_mfma_f32_16x16x32_bf16 v[0:3], v[178:181], v[218:221], v[0:3]
	s_barrier
	s_add_i32 s49, s49, 2
	s_add_u32 s20, s20, 0x100
	s_addc_u32 s21, s21, 0
	s_add_u32 s47, s47, 0x100
	s_addc_u32 s48, s48, 0
	s_cmp_gt_u32 s49, 5
	s_cbranch_scc0 .LBB0_721

; #define PG8_STAGE(bufoff, gbase, voff) do { _Pragma("unroll") for (int _i = 0; _i < 2; ++_i) \
;         __builtin_amdgcn_global_load_lds((const unsigned*)((const char*)(gbase) + (voff)[_i]), (LAS unsigned*)(lds + (bufoff) + ldsw + _i * 8192), 16, 0, 0); } while (0)
; #define PG8_WAIT_V(n) asm volatile("s_waitcnt vmcnt(" #n ")" ::: "memory")
; #define PG8_BAR __builtin_amdgcn_s_barrier()
; template <class Epi>
; __device__ __forceinline__ void gemm_phase(LAS unsigned char* lds, const Gemm g, const StaticOrder& S, const Epi& E) {
;     ...
;     const size_t aslab = g.aslab ? g.aslab : 32 * tstepA;
;     const char* cA = (const char*)g.A + (size_t)(cur.pm >> 5) * aslab + (size_t)(cur.pm & 31) * tstepA; const char* cB = (const char*)g.Bt + (size_t)cur.pn * tstepB;
;     PG8_STAGE(PG8_SB(0, 0), cB, voffB); PG8_STAGE(PG8_SB(0, 1), cB + hstepB, voffB); PG8_STAGE(PG8_SA(0, 0), cA, voffA); PG8_STAGE(PG8_SA(0, 1), cA + hstepA, voffA);
;     if (wr == 1) PG8_BAR;
;     PG8_WAIT_V(2); PG8_BAR;
;     PG8_STAGE(PG8_SB(1, 0), cB + kstep, voffB); PG8_STAGE(PG8_SA(1, 0), cA + kstep, voffA); PG8_STAGE(PG8_SB(1, 1), cB + hstepB + kstep, voffB);
;     PG8_WAIT_V(6); PG8_BAR;
.LBB0_811:
	s_mov_b64 s[16:17], 0x80
	s_and_b32 s36, s5, 3
	s_add_i32 m0, s31, 0x18000
	v_lshl_add_u64 v[6:7], v[6:7], 0, s[16:17]
	s_lshl_b32 s5, s7, 13
	s_lshl_b32 s18, s36, 12
	global_load_lds_dwordx4 v[6:7], off
	v_lshl_add_u64 v[4:5], v[4:5], 0, s[16:17]
	s_add_i32 m0, s31, 0x1a000
	s_add_i32 s37, s31, 0x8000
	s_add_i32 s38, s31, 0xa000
	global_load_lds_dwordx4 v[4:5], off
	v_lshl_add_u64 v[0:1], v[0:1], 0, s[16:17]
	s_mov_b32 m0, s37
	s_add_u32 s8, s26, 0x40080
	global_load_lds_dwordx4 v[0:1], off
	v_lshl_add_u64 v[0:1], v[2:3], 0, s[16:17]
	s_mov_b32 m0, s38
	s_addc_u32 s9, s27, 0
	global_load_lds_dwordx4 v[0:1], off
	s_add_i32 m0, s31, 0x1c000
	v_lshl_add_u64 v[0:1], s[8:9], 0, v[154:155]
	global_load_lds_dwordx4 v[0:1], off
	v_lshl_add_u64 v[0:1], s[8:9], 0, v[158:159]
	s_add_i32 m0, s31, 0x1e000
	s_cmpk_lt_u32 s4, 0x100
	global_load_lds_dwordx4 v[0:1], off
	s_waitcnt vmcnt(8)
	s_barrier
	v_bfe_u32 v0, v8, 4, 2
	v_and_b32_e32 v1, 15, v8
	v_lshlrev_b32_e32 v3, 4, v0
	v_lshl_or_b32 v184, s7, 6, v1
	v_lshl_or_b32 v1, v1, 6, v3
	v_lshlrev_b32_e32 v3, 2, v8
	v_and_b32_e32 v3, 32, v3
	v_readlane_b32 s8, v235, 0
	v_bitop3_b32 v185, v1, s18, v3 bitop3:0xde
	s_cselect_b64 s[18:19], -1, 0
	s_ashr_i32 s39, s74, 31
	s_ashr_i32 s7, s8, 31
	s_sub_u32 s8, 0x400, s8
	v_lshlrev_b32_e32 v2, 3, v0
	v_bitop3_b32 v4, v1, s5, v3 bitop3:0xde
	v_cmp_eq_u32_e64 s[4:5], 0, v0
	s_subb_u32 s9, 0, s7
	v_lshrrev_b32_e32 v1, 1, v9
	v_mul_lo_u32 v0, v11, s6
	s_mov_b32 s7, 0x11000
	v_mad_u64_u32 v[0:1], s[20:21], v1, s7, v[0:1]
	v_or_b32_e32 v0, v0, v10
	v_add_lshl_u32 v0, v0, v12, 1
	v_mov_b32_e32 v1, v155
	s_mov_b64 s[20:21], 0x110080
	v_lshl_add_u64 v[160:161], v[0:1], 0, s[20:21]
	v_lshrrev_b32_e32 v1, 1, v13
	v_mul_lo_u32 v0, v14, s6
	v_mad_u64_u32 v[0:1], s[6:7], v1, s7, v[0:1]
	v_or_b32_e32 v0, v0, v15
	s_waitcnt vmcnt(6)
	v_add_lshl_u32 v0, v0, v16, 1
	v_mov_b32_e32 v1, v155
	v_lshl_add_u64 v[162:163], v[0:1], 0, s[20:21]
	s_add_i32 s41, 0, 0x10000
	s_add_i32 s42, 0, 0x14000
	v_mbcnt_lo_u32_b32 v0, -1, 0
	v_lshl_or_b32 v186, s36, 5, v2
	s_mov_b32 s40, s74
	v_mov_b64_e32 v[164:165], s[8:9]
	v_add_u32_e32 v187, s41, v185
	v_add_u32_e32 v188, s42, v185
	v_add_u32_e32 v190, 0, v4
	v_mbcnt_hi_u32_b32 v191, -1, v0
	s_mov_b32 s43, 0
	s_barrier
	s_branch .LBB0_814

; #define PG8_STAGE(bufoff, gbase, voff) do { _Pragma("unroll") for (int _i = 0; _i < 2; ++_i) \
;         __builtin_amdgcn_global_load_lds((const unsigned*)((const char*)(gbase) + (voff)[_i]), (LAS unsigned*)(lds + (bufoff) + ldsw + _i * 8192), 16, 0, 0); } while (0)
; #define PG8_LDA(dst, b, h) do { _Pragma("unroll") for (int m = 0; m < 4; ++m) _Pragma("unroll") for (int k = 0; k < 2; ++k) dst[m][k] = *(const LAS bf16x8*)(lds + PG8_SA(b, h) + aoff + m * 2048 + k * 1024); } while (0)
; #define PG8_LDB(dst, b, h) do { _Pragma("unroll") for (int n = 0; n < 2; ++n) _Pragma("unroll") for (int k = 0; k < 2; ++k) dst[n][k] = *(const LAS bf16x8*)(lds + PG8_SB(b, h) + boff + n * 2048 + k * 1024); } while (0)
; #define PG8_MMA(ai, bj, At, Bt) do { __builtin_amdgcn_s_setprio(1); _Pragma("unroll") for (int m = 0; m < 4; ++m) _Pragma("unroll") for (int n = 0; n < 2; ++n) _Pragma("unroll") for (int k = 0; k < 2; ++k) \
;         acc[ai][bj][m][n] = __builtin_amdgcn_mfma_f32_16x16x32_bf16(Bt[n][k], At[m][k], acc[ai][bj][m][n], 0, 0, 0); __builtin_amdgcn_s_setprio(0); } while (0)
; template <class Epi>
; __device__ __forceinline__ void gemm_phase(LAS unsigned char* lds, const Gemm g, const StaticOrder& S, const Epi& E) {
;     ...
;         const bool has_next = S.next(ui + 1, nxt);
;         const char* nA = has_next ? (const char*)g.A + (size_t)(nxt.pm >> 5) * aslab + (size_t)(nxt.pm & 31) * tstepA : cA; const char* nB = has_next ? (const char*)g.Bt + (size_t)nxt.pn * tstepB : cB;
;         for (int t = 0; t < nt; t += 2) {
;             const bool last = (t == nt - 2);
;             const char* a1 = cA + (size_t)(t + 1) * kstep;
;             const char* a2 = last ? nA : cA + (size_t)(t + 2) * kstep; const char* b2 = last ? nB : cB + (size_t)(t + 2) * kstep;
;             const char* a3 = a2 + kstep; const char* b3 = b2 + kstep;
;             PG8_LDB(B0, 0, 0); PG8_LDB(B1, 0, 1); PG8_SCHED; PG8_LDA(At, 0, 0); PG8_STAGE(PG8_SA(1, 1), a1 + hstepA, voffA);
;             PG8_WAIT_V(8); PG8_WAIT_L(0); PG8_BAR; PG8_MMA(0, 0, At, B0); PG8_MMA(0, 1, At, B1); PG8_BAR; PG8_SCHED;
;             PG8_LDA(At, 0, 1); PG8_STAGE(PG8_SB(0, 0), b2, voffB); PG8_STAGE(PG8_SB(0, 1), b2 + hstepB, voffB); PG8_STAGE(PG8_SA(0, 0), a2, voffA);
;             PG8_WAIT_V(8); PG8_WAIT_L(0); PG8_BAR; PG8_MMA(1, 0, At, B0); PG8_MMA(1, 1, At, B1); PG8_BAR; PG8_SCHED;
.LBB0_822:
	s_ashr_i32 s21, s20, 31
	s_lshl_b64 s[24:25], s[20:21], 19
	v_readlane_b32 s28, v235, 29
	v_readlane_b32 s29, v235, 30
	s_add_u32 s24, s28, s24
	s_addc_u32 s25, s29, s25
	s_and_b64 s[8:9], s[8:9], exec
	s_cselect_b32 s21, s25, s27
	s_cselect_b32 s46, s24, s26
	s_add_u32 s47, s26, 0x100
	s_addc_u32 s48, s27, 0
	s_mov_b32 s49, -2
	s_waitcnt lgkmcnt(0)
	ds_read_b128 v[128:131], v187
	ds_read_b128 v[132:135], v187 offset:1024
	ds_read_b128 v[136:139], v187 offset:2048
	ds_read_b128 v[140:143], v187 offset:3072
	ds_read_b128 v[144:147], v188
	ds_read_b128 v[148:151], v188 offset:1024
	ds_read_b128 v[166:169], v188 offset:2048
	ds_read_b128 v[170:173], v188 offset:3072
	s_add_u32 s8, s2, 0x100
	s_addc_u32 s9, s3, 0
	s_cmp_eq_u32 s49, 12
	s_cselect_b32 s29, s23, s9
	s_cselect_b32 s28, s22, s8
	s_cselect_b32 s27, s21, s48
	s_cselect_b32 s26, s46, s47
	v_lshl_add_u64 v[182:183], s[2:3], 0, v[160:161]
	s_add_i32 m0, s31, 0xc000
	ds_read_b128 v[174:177], v190
	ds_read_b128 v[178:181], v190 offset:1024
	ds_read_b128 v[192:195], v190 offset:2048
	ds_read_b128 v[198:201], v190 offset:3072
	ds_read_b128 v[202:205], v190 offset:4096
	ds_read_b128 v[206:209], v190 offset:5120
	ds_read_b128 v[210:213], v190 offset:6144
	ds_read_b128 v[214:217], v190 offset:7168
	global_load_lds_dwordx4 v[182:183], off
	v_lshl_add_u64 v[182:183], s[2:3], 0, v[162:163]
	s_add_i32 m0, s31, 0xe000
	s_nop 0
	global_load_lds_dwordx4 v[182:183], off
	s_waitcnt vmcnt(8)
	s_waitcnt lgkmcnt(0)
	s_barrier
	s_waitcnt lgkmcnt(0)
	v_mfma_f32_16x16x32_bf16 v[124:127], v[128:131], v[174:177], 0
	v_mfma_f32_16x16x32_bf16 v[120:123], v[136:139], v[174:177], 0
	v_mfma_f32_16x16x32_bf16 v[108:111], v[128:131], v[192:195], 0
	v_mfma_f32_16x16x32_bf16 v[104:107], v[136:139], v[192:195], 0
	v_mfma_f32_16x16x32_bf16 v[92:95], v[128:131], v[202:205], 0
	v_mfma_f32_16x16x32_bf16 v[88:91], v[136:139], v[202:205], 0
	v_mfma_f32_16x16x32_bf16 v[76:79], v[128:131], v[210:213], 0
	v_mfma_f32_16x16x32_bf16 v[72:75], v[136:139], v[210:213], 0
	v_mfma_f32_16x16x32_bf16 v[124:127], v[132:135], v[178:181], v[124:127]
	v_mfma_f32_16x16x32_bf16 v[120:123], v[140:143], v[178:181], v[120:123]
	v_mfma_f32_16x16x32_bf16 v[108:111], v[132:135], v[198:201], v[108:111]
	v_mfma_f32_16x16x32_bf16 v[104:107], v[140:143], v[198:201], v[104:107]
	v_mfma_f32_16x16x32_bf16 v[92:95], v[132:135], v[206:209], v[92:95]
	v_mfma_f32_16x16x32_bf16 v[88:91], v[140:143], v[206:209], v[88:91]
	v_mfma_f32_16x16x32_bf16 v[76:79], v[132:135], v[214:217], v[76:79]
	v_mfma_f32_16x16x32_bf16 v[72:75], v[140:143], v[214:217], v[72:75]
	v_mfma_f32_16x16x32_bf16 v[116:119], v[144:147], v[174:177], 0
	v_mfma_f32_16x16x32_bf16 v[112:115], v[166:169], v[174:177], 0
	v_mfma_f32_16x16x32_bf16 v[100:103], v[144:147], v[192:195], 0
	v_mfma_f32_16x16x32_bf16 v[96:99], v[166:169], v[192:195], 0
	v_mfma_f32_16x16x32_bf16 v[84:87], v[144:147], v[202:205], 0
	v_mfma_f32_16x16x32_bf16 v[80:83], v[166:169], v[202:205], 0
	v_mfma_f32_16x16x32_bf16 v[68:71], v[144:147], v[210:213], 0
	v_mfma_f32_16x16x32_bf16 v[64:67], v[166:169], v[210:213], 0
	v_mfma_f32_16x16x32_bf16 v[116:119], v[148:151], v[178:181], v[116:119]
	v_mfma_f32_16x16x32_bf16 v[112:115], v[170:173], v[178:181], v[112:115]
	v_mfma_f32_16x16x32_bf16 v[100:103], v[148:151], v[198:201], v[100:103]
	v_mfma_f32_16x16x32_bf16 v[96:99], v[170:173], v[198:201], v[96:99]
	v_mfma_f32_16x16x32_bf16 v[84:87], v[148:151], v[206:209], v[84:87]
	v_mfma_f32_16x16x32_bf16 v[80:83], v[170:173], v[206:209], v[80:83]
	v_mfma_f32_16x16x32_bf16 v[68:71], v[148:151], v[214:217], v[68:71]
	v_mfma_f32_16x16x32_bf16 v[64:67], v[170:173], v[214:217], v[64:67]
	s_barrier
	s_add_i32 s2, s41, s30
	v_lshl_add_u64 v[182:183], s[26:27], 0, v[154:155]
	s_mov_b32 m0, s2
	ds_read_b128 v[174:177], v190 offset:16384
	ds_read_b128 v[178:181], v190 offset:17408
	ds_read_b128 v[192:195], v190 offset:18432
	ds_read_b128 v[198:201], v190 offset:19456
	ds_read_b128 v[202:205], v190 offset:20480
	ds_read_b128 v[206:209], v190 offset:21504
	ds_read_b128 v[210:213], v190 offset:22528
	ds_read_b128 v[214:217], v190 offset:23552
	global_load_lds_dwordx4 v[182:183], off
	s_add_i32 m0, s2, 0x2000
	s_add_u32 s2, s26, 0x40000
	v_lshl_add_u64 v[218:219], s[26:27], 0, v[158:159]
	s_addc_u32 s3, s27, 0
	s_add_i32 s50, s42, s30
	global_load_lds_dwordx4 v[218:219], off
	v_lshl_add_u64 v[220:221], s[2:3], 0, v[154:155]
	s_mov_b32 m0, s50
	v_lshl_add_u64 v[222:223], s[28:29], 0, v[156:157]
	global_load_lds_dwordx4 v[220:221], off
	v_lshl_add_u64 v[220:221], s[2:3], 0, v[158:159]
	s_add_i32 m0, s50, 0x2000
	s_nop 0
	global_load_lds_dwordx4 v[220:221], off
	v_lshl_add_u64 v[220:221], s[28:29], 0, v[152:153]
	s_mov_b32 m0, s31
	s_nop 0
	global_load_lds_dwordx4 v[220:221], off
	s_mov_b32 m0, s33
	s_nop 0
	global_load_lds_dwordx4 v[222:223], off
	s_waitcnt vmcnt(8)
	s_waitcnt lgkmcnt(0)
	s_barrier
; #define PG8_STAGE(bufoff, gbase, voff) do { _Pragma("unroll") for (int _i = 0; _i < 2; ++_i) \
;         __builtin_amdgcn_global_load_lds((const unsigned*)((const char*)(gbase) + (voff)[_i]), (LAS unsigned*)(lds + (bufoff) + ldsw + _i * 8192), 16, 0, 0); } while (0)
; #define PG8_LDA(dst, b, h) do { _Pragma("unroll") for (int m = 0; m < 4; ++m) _Pragma("unroll") for (int k = 0; k < 2; ++k) dst[m][k] = *(const LAS bf16x8*)(lds + PG8_SA(b, h) + aoff + m * 2048 + k * 1024); } while (0)
; #define PG8_LDB(dst, b, h) do { _Pragma("unroll") for (int n = 0; n < 2; ++n) _Pragma("unroll") for (int k = 0; k < 2; ++k) dst[n][k] = *(const LAS bf16x8*)(lds + PG8_SB(b, h) + boff + n * 2048 + k * 1024); } while (0)
; #define PG8_MMA(ai, bj, At, Bt) do { __builtin_amdgcn_s_setprio(1); _Pragma("unroll") for (int m = 0; m < 4; ++m) _Pragma("unroll") for (int n = 0; n < 2; ++n) _Pragma("unroll") for (int k = 0; k < 2; ++k) \
;         acc[ai][bj][m][n] = __builtin_amdgcn_mfma_f32_16x16x32_bf16(Bt[n][k], At[m][k], acc[ai][bj][m][n], 0, 0, 0); __builtin_amdgcn_s_setprio(0); } while (0)
; #define PG8_WAIT_V(n) asm volatile("s_waitcnt vmcnt(" #n ")" ::: "memory")
; #define PG8_WAIT_L(n) asm volatile("s_waitcnt lgkmcnt(" #n ")" ::: "memory")
; #define PG8_BAR __builtin_amdgcn_s_barrier()
; #define PG8_SCHED __builtin_amdgcn_sched_barrier(0)
; template <class Epi>
; __device__ __forceinline__ void gemm_phase(LAS unsigned char* lds, const Gemm g, const StaticOrder& S, const Epi& E) {
;     ...
;             PG8_WAIT_V(8); PG8_WAIT_L(0); PG8_BAR; PG8_MMA(1, 0, At, B0); PG8_MMA(1, 1, At, B1); PG8_BAR; PG8_SCHED;
;             PG8_LDB(B0, 1, 0); PG8_LDB(B1, 1, 1); PG8_SCHED; PG8_LDA(At, 1, 0); PG8_STAGE(PG8_SA(0, 1), a2 + hstepA, voffA);
;             PG8_WAIT_V(8); PG8_WAIT_L(0); PG8_BAR; PG8_MMA(0, 0, At, B0); PG8_MMA(0, 1, At, B1); PG8_BAR; PG8_SCHED;
;             PG8_LDA(At, 1, 1); PG8_STAGE(PG8_SB(1, 0), b3, voffB); PG8_STAGE(PG8_SB(1, 1), b3 + hstepB, voffB); PG8_STAGE(PG8_SA(1, 0), a3, voffA);
;             PG8_WAIT_V(8); PG8_WAIT_L(0); PG8_BAR; PG8_MMA(1, 0, At, B0); PG8_MMA(1, 1, At, B1); PG8_BAR; PG8_SCHED;
	s_waitcnt lgkmcnt(0)
	v_mfma_f32_16x16x32_bf16 v[60:63], v[128:131], v[174:177], 0
	v_mfma_f32_16x16x32_bf16 v[56:59], v[136:139], v[174:177], 0
	v_mfma_f32_16x16x32_bf16 v[44:47], v[128:131], v[192:195], 0
	v_mfma_f32_16x16x32_bf16 v[40:43], v[136:139], v[192:195], 0
	v_mfma_f32_16x16x32_bf16 v[28:31], v[128:131], v[202:205], 0
	v_mfma_f32_16x16x32_bf16 v[24:27], v[136:139], v[202:205], 0
	v_mfma_f32_16x16x32_bf16 v[12:15], v[128:131], v[210:213], 0
	v_mfma_f32_16x16x32_bf16 v[8:11], v[136:139], v[210:213], 0
	v_mfma_f32_16x16x32_bf16 v[60:63], v[132:135], v[178:181], v[60:63]
	v_mfma_f32_16x16x32_bf16 v[56:59], v[140:143], v[178:181], v[56:59]
	v_mfma_f32_16x16x32_bf16 v[44:47], v[132:135], v[198:201], v[44:47]
	v_mfma_f32_16x16x32_bf16 v[40:43], v[140:143], v[198:201], v[40:43]
	v_mfma_f32_16x16x32_bf16 v[28:31], v[132:135], v[206:209], v[28:31]
	v_mfma_f32_16x16x32_bf16 v[24:27], v[140:143], v[206:209], v[24:27]
	v_mfma_f32_16x16x32_bf16 v[12:15], v[132:135], v[214:217], v[12:15]
	v_mfma_f32_16x16x32_bf16 v[8:11], v[140:143], v[214:217], v[8:11]
	v_mfma_f32_16x16x32_bf16 v[52:55], v[144:147], v[174:177], 0
	v_mfma_f32_16x16x32_bf16 v[48:51], v[166:169], v[174:177], 0
	v_mfma_f32_16x16x32_bf16 v[36:39], v[144:147], v[192:195], 0
	v_mfma_f32_16x16x32_bf16 v[32:35], v[166:169], v[192:195], 0
	v_mfma_f32_16x16x32_bf16 v[20:23], v[144:147], v[202:205], 0
	v_mfma_f32_16x16x32_bf16 v[16:19], v[166:169], v[202:205], 0
	v_mfma_f32_16x16x32_bf16 v[4:7], v[144:147], v[210:213], 0
	v_mfma_f32_16x16x32_bf16 v[0:3], v[166:169], v[210:213], 0
	v_mfma_f32_16x16x32_bf16 v[52:55], v[148:151], v[178:181], v[52:55]
	v_mfma_f32_16x16x32_bf16 v[48:51], v[170:173], v[178:181], v[48:51]
	v_mfma_f32_16x16x32_bf16 v[36:39], v[148:151], v[198:201], v[36:39]
	v_mfma_f32_16x16x32_bf16 v[32:35], v[170:173], v[198:201], v[32:35]
	v_mfma_f32_16x16x32_bf16 v[20:23], v[148:151], v[206:209], v[20:23]
	v_mfma_f32_16x16x32_bf16 v[16:19], v[170:173], v[206:209], v[16:19]
	v_mfma_f32_16x16x32_bf16 v[4:7], v[148:151], v[214:217], v[4:7]
	v_mfma_f32_16x16x32_bf16 v[0:3], v[170:173], v[214:217], v[0:3]
	s_barrier
	s_add_i32 s50, 0, 0x18000
	s_add_i32 s51, 0, 0x1c000
	v_add_u32_e32 v140, s50, v185
	v_add_u32_e32 v170, s51, v185
	ds_read_b128 v[128:131], v140
	ds_read_b128 v[132:135], v140 offset:1024
	ds_read_b128 v[136:139], v140 offset:2048
	ds_read_b128 v[140:143], v140 offset:3072
	ds_read_b128 v[144:147], v170
	ds_read_b128 v[148:151], v170 offset:1024
	ds_read_b128 v[166:169], v170 offset:2048
	ds_read_b128 v[170:173], v170 offset:3072
	s_add_u32 s2, s28, 0x110000
	s_addc_u32 s3, s29, 0
	s_mov_b32 m0, s34
	v_lshl_add_u64 v[224:225], s[2:3], 0, v[152:153]
	ds_read_b128 v[174:177], v190 offset:32768
	ds_read_b128 v[178:181], v190 offset:33792
	ds_read_b128 v[192:195], v190 offset:34816
	ds_read_b128 v[198:201], v190 offset:35840
	ds_read_b128 v[202:205], v190 offset:36864
	ds_read_b128 v[206:209], v190 offset:37888
	ds_read_b128 v[210:213], v190 offset:38912
	ds_read_b128 v[214:217], v190 offset:39936
	global_load_lds_dwordx4 v[224:225], off
	v_lshl_add_u64 v[224:225], s[2:3], 0, v[156:157]
	s_mov_b32 m0, s35
	s_nop 0
	global_load_lds_dwordx4 v[224:225], off
	s_waitcnt vmcnt(8)
	s_waitcnt lgkmcnt(0)
	s_barrier
	s_waitcnt lgkmcnt(0)
	v_mfma_f32_16x16x32_bf16 v[124:127], v[128:131], v[174:177], v[124:127]
	v_mfma_f32_16x16x32_bf16 v[120:123], v[136:139], v[174:177], v[120:123]
	v_mfma_f32_16x16x32_bf16 v[108:111], v[128:131], v[192:195], v[108:111]
	v_mfma_f32_16x16x32_bf16 v[104:107], v[136:139], v[192:195], v[104:107]
	v_mfma_f32_16x16x32_bf16 v[92:95], v[128:131], v[202:205], v[92:95]
	v_mfma_f32_16x16x32_bf16 v[88:91], v[136:139], v[202:205], v[88:91]
	v_mfma_f32_16x16x32_bf16 v[76:79], v[128:131], v[210:213], v[76:79]
	v_mfma_f32_16x16x32_bf16 v[72:75], v[136:139], v[210:213], v[72:75]
	v_mfma_f32_16x16x32_bf16 v[124:127], v[132:135], v[178:181], v[124:127]
	v_mfma_f32_16x16x32_bf16 v[120:123], v[140:143], v[178:181], v[120:123]
	v_mfma_f32_16x16x32_bf16 v[108:111], v[132:135], v[198:201], v[108:111]
	v_mfma_f32_16x16x32_bf16 v[104:107], v[140:143], v[198:201], v[104:107]
	v_mfma_f32_16x16x32_bf16 v[92:95], v[132:135], v[206:209], v[92:95]
	v_mfma_f32_16x16x32_bf16 v[88:91], v[140:143], v[206:209], v[88:91]
	v_mfma_f32_16x16x32_bf16 v[76:79], v[132:135], v[214:217], v[76:79]
	v_mfma_f32_16x16x32_bf16 v[72:75], v[140:143], v[214:217], v[72:75]
	v_mfma_f32_16x16x32_bf16 v[116:119], v[144:147], v[174:177], v[116:119]
	v_mfma_f32_16x16x32_bf16 v[112:115], v[166:169], v[174:177], v[112:115]
	v_mfma_f32_16x16x32_bf16 v[100:103], v[144:147], v[192:195], v[100:103]
	v_mfma_f32_16x16x32_bf16 v[96:99], v[166:169], v[192:195], v[96:99]
	v_mfma_f32_16x16x32_bf16 v[84:87], v[144:147], v[202:205], v[84:87]
	v_mfma_f32_16x16x32_bf16 v[80:83], v[166:169], v[202:205], v[80:83]
	v_mfma_f32_16x16x32_bf16 v[68:71], v[144:147], v[210:213], v[68:71]
	v_mfma_f32_16x16x32_bf16 v[64:67], v[166:169], v[210:213], v[64:67]
	v_mfma_f32_16x16x32_bf16 v[116:119], v[148:151], v[178:181], v[116:119]
	v_mfma_f32_16x16x32_bf16 v[112:115], v[170:173], v[178:181], v[112:115]
	v_mfma_f32_16x16x32_bf16 v[100:103], v[148:151], v[198:201], v[100:103]
	v_mfma_f32_16x16x32_bf16 v[96:99], v[170:173], v[198:201], v[96:99]
	v_mfma_f32_16x16x32_bf16 v[84:87], v[148:151], v[206:209], v[84:87]
	v_mfma_f32_16x16x32_bf16 v[80:83], v[170:173], v[206:209], v[80:83]
	v_mfma_f32_16x16x32_bf16 v[68:71], v[148:151], v[214:217], v[68:71]
	v_mfma_f32_16x16x32_bf16 v[64:67], v[170:173], v[214:217], v[64:67]
	s_barrier
; #define PG8_STAGE(bufoff, gbase, voff) do { _Pragma("unroll") for (int _i = 0; _i < 2; ++_i) \
;         __builtin_amdgcn_global_load_lds((const unsigned*)((const char*)(gbase) + (voff)[_i]), (LAS unsigned*)(lds + (bufoff) + ldsw + _i * 8192), 16, 0, 0); } while (0)
; #define PG8_LDA(dst, b, h) do { _Pragma("unroll") for (int m = 0; m < 4; ++m) _Pragma("unroll") for (int k = 0; k < 2; ++k) dst[m][k] = *(const LAS bf16x8*)(lds + PG8_SA(b, h) + aoff + m * 2048 + k * 1024); } while (0)
; #define PG8_MMA(ai, bj, At, Bt) do { __builtin_amdgcn_s_setprio(1); _Pragma("unroll") for (int m = 0; m < 4; ++m) _Pragma("unroll") for (int n = 0; n < 2; ++n) _Pragma("unroll") for (int k = 0; k < 2; ++k) \
;         acc[ai][bj][m][n] = __builtin_amdgcn_mfma_f32_16x16x32_bf16(Bt[n][k], At[m][k], acc[ai][bj][m][n], 0, 0, 0); __builtin_amdgcn_s_setprio(0); } while (0)
; #define PG8_WAIT_V(n) asm volatile("s_waitcnt vmcnt(" #n ")" ::: "memory")
; #define PG8_WAIT_L(n) asm volatile("s_waitcnt lgkmcnt(" #n ")" ::: "memory")
; #define PG8_BAR __builtin_amdgcn_s_barrier()
; #define PG8_SCHED __builtin_amdgcn_sched_barrier(0)
; template <class Epi>
; __device__ __forceinline__ void gemm_phase(LAS unsigned char* lds, const Gemm g, const StaticOrder& S, const Epi& E) {
;     ...
;             PG8_LDA(At, 1, 1); PG8_STAGE(PG8_SB(1, 0), b3, voffB); PG8_STAGE(PG8_SB(1, 1), b3 + hstepB, voffB); PG8_STAGE(PG8_SA(1, 0), a3, voffA);
;             PG8_WAIT_V(8); PG8_WAIT_L(0); PG8_BAR; PG8_MMA(1, 0, At, B0); PG8_MMA(1, 1, At, B1); PG8_BAR; PG8_SCHED;
;         }
	s_add_i32 s2, s50, s30
	v_lshl_add_u64 v[182:183], v[182:183], 0, s[16:17]
	s_mov_b32 m0, s2
	ds_read_b128 v[174:177], v190 offset:49152
	ds_read_b128 v[178:181], v190 offset:50176
	ds_read_b128 v[192:195], v190 offset:51200
	ds_read_b128 v[198:201], v190 offset:52224
	ds_read_b128 v[202:205], v190 offset:53248
	ds_read_b128 v[206:209], v190 offset:54272
	ds_read_b128 v[210:213], v190 offset:55296
	ds_read_b128 v[214:217], v190 offset:56320
	global_load_lds_dwordx4 v[182:183], off
	s_add_i32 m0, s2, 0x2000
	s_add_u32 s2, s26, 0x40080
	v_lshl_add_u64 v[182:183], v[218:219], 0, s[16:17]
	s_addc_u32 s3, s27, 0
	s_add_i32 s26, s51, s30
	global_load_lds_dwordx4 v[182:183], off
	v_lshl_add_u64 v[182:183], s[2:3], 0, v[154:155]
	s_mov_b32 m0, s26
	s_nop 0
	global_load_lds_dwordx4 v[182:183], off
	v_lshl_add_u64 v[182:183], s[2:3], 0, v[158:159]
	s_add_i32 m0, s26, 0x2000
	s_nop 0
	global_load_lds_dwordx4 v[182:183], off
	v_lshl_add_u64 v[182:183], v[220:221], 0, s[16:17]
	s_mov_b32 m0, s37
	s_nop 0
	global_load_lds_dwordx4 v[182:183], off
	v_lshl_add_u64 v[182:183], v[222:223], 0, s[16:17]
	s_mov_b32 m0, s38
	s_nop 0
	global_load_lds_dwordx4 v[182:183], off
	s_waitcnt vmcnt(8)
	s_waitcnt lgkmcnt(0)
	s_barrier
	s_waitcnt lgkmcnt(0)
	v_mfma_f32_16x16x32_bf16 v[60:63], v[128:131], v[174:177], v[60:63]
	v_mfma_f32_16x16x32_bf16 v[56:59], v[136:139], v[174:177], v[56:59]
	v_mfma_f32_16x16x32_bf16 v[44:47], v[128:131], v[192:195], v[44:47]
	v_mfma_f32_16x16x32_bf16 v[40:43], v[136:139], v[192:195], v[40:43]
	v_mfma_f32_16x16x32_bf16 v[28:31], v[128:131], v[202:205], v[28:31]
	v_mfma_f32_16x16x32_bf16 v[24:27], v[136:139], v[202:205], v[24:27]
	v_mfma_f32_16x16x32_bf16 v[12:15], v[128:131], v[210:213], v[12:15]
	v_mfma_f32_16x16x32_bf16 v[8:11], v[136:139], v[210:213], v[8:11]
	v_mfma_f32_16x16x32_bf16 v[60:63], v[132:135], v[178:181], v[60:63]
	v_mfma_f32_16x16x32_bf16 v[56:59], v[140:143], v[178:181], v[56:59]
	v_mfma_f32_16x16x32_bf16 v[44:47], v[132:135], v[198:201], v[44:47]
	v_mfma_f32_16x16x32_bf16 v[40:43], v[140:143], v[198:201], v[40:43]
	v_mfma_f32_16x16x32_bf16 v[28:31], v[132:135], v[206:209], v[28:31]
	v_mfma_f32_16x16x32_bf16 v[24:27], v[140:143], v[206:209], v[24:27]
	v_mfma_f32_16x16x32_bf16 v[12:15], v[132:135], v[214:217], v[12:15]
	v_mfma_f32_16x16x32_bf16 v[8:11], v[140:143], v[214:217], v[8:11]
	v_mfma_f32_16x16x32_bf16 v[52:55], v[144:147], v[174:177], v[52:55]
	v_mfma_f32_16x16x32_bf16 v[48:51], v[166:169], v[174:177], v[48:51]
	v_mfma_f32_16x16x32_bf16 v[36:39], v[144:147], v[192:195], v[36:39]
	v_mfma_f32_16x16x32_bf16 v[32:35], v[166:169], v[192:195], v[32:35]
	v_mfma_f32_16x16x32_bf16 v[20:23], v[144:147], v[202:205], v[20:23]
	v_mfma_f32_16x16x32_bf16 v[16:19], v[166:169], v[202:205], v[16:19]
	v_mfma_f32_16x16x32_bf16 v[4:7], v[144:147], v[210:213], v[4:7]
	v_mfma_f32_16x16x32_bf16 v[0:3], v[166:169], v[210:213], v[0:3]
	v_mfma_f32_16x16x32_bf16 v[52:55], v[148:151], v[178:181], v[52:55]
	v_mfma_f32_16x16x32_bf16 v[48:51], v[170:173], v[178:181], v[48:51]
	v_mfma_f32_16x16x32_bf16 v[36:39], v[148:151], v[198:201], v[36:39]
	v_mfma_f32_16x16x32_bf16 v[32:35], v[170:173], v[198:201], v[32:35]
	v_mfma_f32_16x16x32_bf16 v[20:23], v[148:151], v[206:209], v[20:23]
	v_mfma_f32_16x16x32_bf16 v[16:19], v[170:173], v[206:209], v[16:19]
	v_mfma_f32_16x16x32_bf16 v[4:7], v[148:151], v[214:217], v[4:7]
	v_mfma_f32_16x16x32_bf16 v[0:3], v[170:173], v[214:217], v[0:3]
	s_barrier
	s_add_i32 s49, s49, 2
	s_add_u32 s47, s47, 0x100
	s_addc_u32 s48, s48, 0
	s_cmp_gt_u32 s49, 13
	s_mov_b64 s[2:3], s[8:9]
	s_cbranch_scc0 .LBB0_823

; #define PG8_STAGE(bufoff, gbase, voff) do { _Pragma("unroll") for (int _i = 0; _i < 2; ++_i) \
;         __builtin_amdgcn_global_load_lds((const unsigned*)((const char*)(gbase) + (voff)[_i]), (LAS unsigned*)(lds + (bufoff) + ldsw + _i * 8192), 16, 0, 0); } while (0)
; #define PG8_WAIT_V(n) asm volatile("s_waitcnt vmcnt(" #n ")" ::: "memory")
; #define PG8_BAR __builtin_amdgcn_s_barrier()
; template <class Epi>
; __device__ __forceinline__ void gemm_phase(LAS unsigned char* lds, const Gemm g, const StaticOrder& S, const Epi& E) {
;     ...
;     const int wid = __builtin_amdgcn_readfirstlane(tid >> 6), lane = tid & 63, wr = wid >> 2, wc = wid & 3, fr = lane & 15, fq = lane >> 4;
;     const int K = g.K, nt = K / BK, lda = g.lda;
;     unsigned voffA[2], voffB[2];
; #pragma unroll
;     for (int i = 0; i < 2; ++i) { int R, C; stage_rc(tid * 16 + i * 8192, R, C); const int Rb = Epi::PERM ? ((R & ~31) + perm32(R & 31)) : R;
;         voffA[i] = (unsigned)(R * lda + C) * 2u; voffB[i] = (unsigned)(Rb * K + C) * 2u; }
;     const size_t kstep = (size_t)(BK * 2);
;     const size_t hstepA = (size_t)HALF * lda * 2, hstepB = (size_t)HALF * K * 2;
;     const size_t tstepA = 2 * hstepA, tstepB = 2 * hstepB;
;     const unsigned ldsw = (unsigned)wid * 1024u;
;     const int aoff = lds_byte(wr * 64 + fr, fq * 8), boff = lds_byte(wc * 32 + fr, fq * 8);
;     ...
;     PG8_STAGE(PG8_SB(0, 0), cB, voffB); PG8_STAGE(PG8_SB(0, 1), cB + hstepB, voffB); PG8_STAGE(PG8_SA(0, 0), cA, voffA); PG8_STAGE(PG8_SA(0, 1), cA + hstepA, voffA);
;     if (wr == 1) PG8_BAR;
;     PG8_WAIT_V(2); PG8_BAR;
;     PG8_STAGE(PG8_SB(1, 0), cB + kstep, voffB); PG8_STAGE(PG8_SA(1, 0), cA + kstep, voffA); PG8_STAGE(PG8_SB(1, 1), cB + hstepB + kstep, voffB);
;     PG8_WAIT_V(6); PG8_BAR;
.LBB0_923:
	s_lshl_b32 s6, s6, 5
	s_lshl_b32 s29, s7, 6
	s_lshl_b32 s13, s7, 13
	s_and_b32 s14, s6, 0x60
	s_mov_b64 s[6:7], 0x80
	s_add_i32 m0, s22, 0x18000
	v_lshl_add_u64 v[6:7], v[6:7], 0, s[6:7]
	s_lshl_b32 s15, s14, 7
	global_load_lds_dwordx4 v[6:7], off
	v_lshl_add_u64 v[2:3], v[2:3], 0, s[6:7]
	s_add_i32 m0, s22, 0x1a000
	s_add_i32 s30, s22, 0x8000
	s_add_i32 s31, s22, 0xa000
	global_load_lds_dwordx4 v[2:3], off
	v_lshl_add_u64 v[0:1], v[0:1], 0, s[6:7]
	s_mov_b32 m0, s30
	s_add_u32 s8, s2, 0x40080
	global_load_lds_dwordx4 v[0:1], off
	v_lshl_add_u64 v[0:1], v[4:5], 0, s[6:7]
	s_mov_b32 m0, s31
	s_addc_u32 s9, s3, 0
	global_load_lds_dwordx4 v[0:1], off
	s_add_i32 m0, s22, 0x1c000
	v_lshl_add_u64 v[0:1], s[8:9], 0, v[132:133]
	global_load_lds_dwordx4 v[0:1], off
	v_lshl_add_u64 v[0:1], s[8:9], 0, v[128:129]
	s_add_i32 m0, s22, 0x1e000
	v_and_b32_e32 v150, 15, v10
	global_load_lds_dwordx4 v[0:1], off
	s_waitcnt vmcnt(8)
	s_barrier
	v_bfe_u32 v0, v10, 4, 2
	v_lshlrev_b32_e32 v136, 4, v0
	v_lshlrev_b32_e32 v2, 2, v10
	v_lshl_or_b32 v152, v0, 3, s14
	v_lshlrev_b32_e32 v0, 14, v13
	v_lshl_or_b32 v1, v150, 6, v136
	v_and_b32_e32 v2, 32, v2
	v_and_b32_e32 v0, 0xffff8000, v0
	v_bitop3_b32 v3, v1, s13, v2 bitop3:0xde
	v_bitop3_b32 v151, v1, s15, v2 bitop3:0xde
	v_lshl_add_u32 v0, v12, 11, v0
	v_and_b32_e32 v1, 1, v13
	v_lshl_or_b32 v0, v1, 6, v0
	v_lshl_add_u32 v140, v14, 1, v0
	v_lshlrev_b32_e32 v0, 14, v8
	s_cmpk_lt_u32 s5, 0x100
	v_and_b32_e32 v0, 0xffff8000, v0
	s_sext_i32_i16 s42, s4
	s_cselect_b64 s[8:9], -1, 0
	s_ashr_i32 s33, s74, 31
	v_readlane_b32 s4, v235, 0
	v_lshl_add_u32 v0, v9, 11, v0
	v_and_b32_e32 v1, 1, v8
	s_waitcnt vmcnt(6)
	s_sub_u32 s4, 0x1600, s4
	v_lshl_or_b32 v0, v1, 6, v0
	s_subb_u32 s5, 0, s12
	v_lshl_add_u32 v142, v11, 1, v0
	s_add_i32 s35, 0, 0x10000
	s_add_i32 s36, 0, 0x14000
	v_mbcnt_lo_u32_b32 v0, -1, 0
	v_lshl_add_u64 v[138:139], s[10:11], 0, v[136:137]
	s_mov_b32 s34, s74
	v_mov_b32_e32 v141, v137
	v_mov_b32_e32 v143, v137
	v_mov_b64_e32 v[144:145], s[4:5]
	v_add_u32_e32 v153, s35, v151
	v_add_u32_e32 v154, s36, v151
	v_add_u32_e32 v155, 0, v3
	v_mbcnt_hi_u32_b32 v156, -1, v0
	v_mov_b32_e32 v157, 0x358637bd
	s_mov_b32 s37, 0x4400000
	s_mov_b32 s38, 0x2d000
	s_mov_b32 s39, 0x43000
	v_mov_b32_e32 v158, 0x1fcf
	s_barrier
	s_branch .LBB0_926

; #define PG8_STAGE(bufoff, gbase, voff) do { _Pragma("unroll") for (int _i = 0; _i < 2; ++_i) \
;         __builtin_amdgcn_global_load_lds((const unsigned*)((const char*)(gbase) + (voff)[_i]), (LAS unsigned*)(lds + (bufoff) + ldsw + _i * 8192), 16, 0, 0); } while (0)
; #define PG8_LDA(dst, b, h) do { _Pragma("unroll") for (int m = 0; m < 4; ++m) _Pragma("unroll") for (int k = 0; k < 2; ++k) dst[m][k] = *(const LAS bf16x8*)(lds + PG8_SA(b, h) + aoff + m * 2048 + k * 1024); } while (0)
; #define PG8_LDB(dst, b, h) do { _Pragma("unroll") for (int n = 0; n < 2; ++n) _Pragma("unroll") for (int k = 0; k < 2; ++k) dst[n][k] = *(const LAS bf16x8*)(lds + PG8_SB(b, h) + boff + n * 2048 + k * 1024); } while (0)
; #define PG8_MMA(ai, bj, At, Bt) do { __builtin_amdgcn_s_setprio(1); _Pragma("unroll") for (int m = 0; m < 4; ++m) _Pragma("unroll") for (int n = 0; n < 2; ++n) _Pragma("unroll") for (int k = 0; k < 2; ++k) \
;         acc[ai][bj][m][n] = __builtin_amdgcn_mfma_f32_16x16x32_bf16(Bt[n][k], At[m][k], acc[ai][bj][m][n], 0, 0, 0); __builtin_amdgcn_s_setprio(0); } while (0)
; template <class Epi>
; __device__ __forceinline__ void gemm_phase(LAS unsigned char* lds, const Gemm g, const StaticOrder& S, const Epi& E) {
;     ...
;         const bool has_next = S.next(ui + 1, nxt);
;         const char* nA = has_next ? (const char*)g.A + (size_t)(nxt.pm >> 5) * aslab + (size_t)(nxt.pm & 31) * tstepA : cA; const char* nB = has_next ? (const char*)g.Bt + (size_t)nxt.pn * tstepB : cB;
;         for (int t = 0; t < nt; t += 2) {
;             const bool last = (t == nt - 2);
;             const char* a1 = cA + (size_t)(t + 1) * kstep;
;             const char* a2 = last ? nA : cA + (size_t)(t + 2) * kstep; const char* b2 = last ? nB : cB + (size_t)(t + 2) * kstep;
;             const char* a3 = a2 + kstep; const char* b3 = b2 + kstep;
;             PG8_LDB(B0, 0, 0); PG8_LDB(B1, 0, 1); PG8_SCHED; PG8_LDA(At, 0, 0); PG8_STAGE(PG8_SA(1, 1), a1 + hstepA, voffA);
;             PG8_WAIT_V(8); PG8_WAIT_L(0); PG8_BAR; PG8_MMA(0, 0, At, B0); PG8_MMA(0, 1, At, B1); PG8_BAR; PG8_SCHED;
;             PG8_LDA(At, 0, 1); PG8_STAGE(PG8_SB(0, 0), b2, voffB); PG8_STAGE(PG8_SB(0, 1), b2 + hstepB, voffB); PG8_STAGE(PG8_SA(0, 0), a2, voffA);
;             PG8_WAIT_V(8); PG8_WAIT_L(0); PG8_BAR; PG8_MMA(1, 0, At, B0); PG8_MMA(1, 1, At, B1); PG8_BAR; PG8_SCHED;
.LBB0_928:
	s_ashr_i32 s12, s40, 5
	s_ashr_i32 s13, s12, 31
	s_lshl_b64 s[12:13], s[12:13], 24
	v_readlane_b32 s14, v235, 38
	v_readlane_b32 s15, v235, 39
	s_add_u32 s11, s14, s12
	s_addc_u32 s13, s15, s13
	s_lshl_b32 s12, s40, 19
	s_and_b32 s12, s12, 0xf80000
	s_add_u32 s12, s11, s12
	s_addc_u32 s13, s13, 0
	s_and_b64 s[14:15], s[4:5], exec
	s_cselect_b32 s43, s13, s17
	s_cselect_b32 s44, s12, s16
	s_ashr_i32 s11, s10, 31
	s_lshl_b64 s[14:15], s[10:11], 19
	v_readlane_b32 s18, v235, 31
	v_readlane_b32 s19, v235, 32
	s_add_u32 s14, s18, s14
	s_addc_u32 s15, s19, s15
	s_and_b64 s[18:19], s[4:5], exec
	s_cselect_b32 s11, s15, s3
	s_cselect_b32 s45, s14, s2
	s_add_u32 s16, s16, 0x40080
	s_addc_u32 s17, s17, 0
	s_add_u32 s46, s2, 0x100
	s_addc_u32 s47, s3, 0
	s_mov_b32 s48, -2
	ds_read_b128 v[146:149], v153
	ds_read_b128 v[160:163], v153 offset:1024
	ds_read_b128 v[164:167], v153 offset:2048
	ds_read_b128 v[168:171], v153 offset:3072
	ds_read_b128 v[172:175], v154
	ds_read_b128 v[176:179], v154 offset:1024
	ds_read_b128 v[180:183], v154 offset:2048
	ds_read_b128 v[184:187], v154 offset:3072
	s_add_u32 s2, s16, 0xfffc0080
	s_addc_u32 s3, s17, -1
	s_cmp_eq_u32 s48, 12
	s_cselect_b32 s19, s43, s3
	s_cselect_b32 s18, s44, s2
	s_cselect_b32 s3, s11, s47
	s_cselect_b32 s2, s45, s46
	v_lshl_add_u64 v[194:195], s[16:17], 0, v[140:141]
	s_add_i32 m0, s22, 0xc000
	ds_read_b128 v[190:193], v155
	ds_read_b128 v[198:201], v155 offset:1024
	ds_read_b128 v[202:205], v155 offset:2048
	ds_read_b128 v[206:209], v155 offset:3072
	ds_read_b128 v[210:213], v155 offset:4096
	ds_read_b128 v[214:217], v155 offset:5120
	ds_read_b128 v[218:221], v155 offset:6144
	ds_read_b128 v[222:225], v155 offset:7168
	global_load_lds_dwordx4 v[194:195], off
	v_lshl_add_u64 v[194:195], s[16:17], 0, v[142:143]
	s_add_i32 m0, s22, 0xe000
	s_nop 0
	global_load_lds_dwordx4 v[194:195], off
	s_waitcnt vmcnt(8)
	s_waitcnt lgkmcnt(0)
	s_barrier
	s_waitcnt lgkmcnt(0)
	v_mfma_f32_16x16x32_bf16 v[124:127], v[146:149], v[190:193], 0
	v_mfma_f32_16x16x32_bf16 v[116:119], v[164:167], v[190:193], 0
	v_mfma_f32_16x16x32_bf16 v[108:111], v[146:149], v[202:205], 0
	v_mfma_f32_16x16x32_bf16 v[100:103], v[164:167], v[202:205], 0
	v_mfma_f32_16x16x32_bf16 v[92:95], v[146:149], v[210:213], 0
	v_mfma_f32_16x16x32_bf16 v[84:87], v[164:167], v[210:213], 0
	v_mfma_f32_16x16x32_bf16 v[76:79], v[146:149], v[218:221], 0
	v_mfma_f32_16x16x32_bf16 v[68:71], v[164:167], v[218:221], 0
	v_mfma_f32_16x16x32_bf16 v[124:127], v[160:163], v[198:201], v[124:127]
	v_mfma_f32_16x16x32_bf16 v[116:119], v[168:171], v[198:201], v[116:119]
	v_mfma_f32_16x16x32_bf16 v[108:111], v[160:163], v[206:209], v[108:111]
	v_mfma_f32_16x16x32_bf16 v[100:103], v[168:171], v[206:209], v[100:103]
	v_mfma_f32_16x16x32_bf16 v[92:95], v[160:163], v[214:217], v[92:95]
	v_mfma_f32_16x16x32_bf16 v[84:87], v[168:171], v[214:217], v[84:87]
	v_mfma_f32_16x16x32_bf16 v[76:79], v[160:163], v[222:225], v[76:79]
	v_mfma_f32_16x16x32_bf16 v[68:71], v[168:171], v[222:225], v[68:71]
	v_mfma_f32_16x16x32_bf16 v[120:123], v[172:175], v[190:193], 0
	v_mfma_f32_16x16x32_bf16 v[112:115], v[180:183], v[190:193], 0
	v_mfma_f32_16x16x32_bf16 v[104:107], v[172:175], v[202:205], 0
	v_mfma_f32_16x16x32_bf16 v[96:99], v[180:183], v[202:205], 0
	v_mfma_f32_16x16x32_bf16 v[88:91], v[172:175], v[210:213], 0
	v_mfma_f32_16x16x32_bf16 v[80:83], v[180:183], v[210:213], 0
	v_mfma_f32_16x16x32_bf16 v[72:75], v[172:175], v[218:221], 0
	v_mfma_f32_16x16x32_bf16 v[64:67], v[180:183], v[218:221], 0
	v_mfma_f32_16x16x32_bf16 v[120:123], v[176:179], v[198:201], v[120:123]
	v_mfma_f32_16x16x32_bf16 v[112:115], v[184:187], v[198:201], v[112:115]
	v_mfma_f32_16x16x32_bf16 v[104:107], v[176:179], v[206:209], v[104:107]
	v_mfma_f32_16x16x32_bf16 v[96:99], v[184:187], v[206:209], v[96:99]
	v_mfma_f32_16x16x32_bf16 v[88:91], v[176:179], v[214:217], v[88:91]
	v_mfma_f32_16x16x32_bf16 v[80:83], v[184:187], v[214:217], v[80:83]
	v_mfma_f32_16x16x32_bf16 v[72:75], v[176:179], v[222:225], v[72:75]
	v_mfma_f32_16x16x32_bf16 v[64:67], v[184:187], v[222:225], v[64:67]
	s_barrier
	s_add_i32 s49, s35, s20
	v_lshl_add_u64 v[194:195], s[2:3], 0, v[132:133]
	s_mov_b32 m0, s49
	ds_read_b128 v[190:193], v155 offset:16384
	ds_read_b128 v[198:201], v155 offset:17408
	ds_read_b128 v[202:205], v155 offset:18432
	ds_read_b128 v[206:209], v155 offset:19456
	ds_read_b128 v[210:213], v155 offset:20480
	ds_read_b128 v[214:217], v155 offset:21504
	ds_read_b128 v[218:221], v155 offset:22528
	ds_read_b128 v[222:225], v155 offset:23552
	global_load_lds_dwordx4 v[194:195], off
	s_add_i32 m0, s49, 0x2000
	s_add_u32 s50, s2, 0x40000
	v_lshl_add_u64 v[226:227], s[2:3], 0, v[128:129]
	s_addc_u32 s51, s3, 0
	s_add_i32 s49, s36, s20
	global_load_lds_dwordx4 v[226:227], off
	v_lshl_add_u64 v[228:229], s[50:51], 0, v[132:133]
	s_mov_b32 m0, s49
	v_lshl_add_u64 v[230:231], s[18:19], 0, v[130:131]
	global_load_lds_dwordx4 v[228:229], off
	v_lshl_add_u64 v[228:229], s[50:51], 0, v[128:129]
	s_add_i32 m0, s49, 0x2000
	s_nop 0
	global_load_lds_dwordx4 v[228:229], off
	v_lshl_add_u64 v[228:229], s[18:19], 0, v[134:135]
	s_mov_b32 m0, s22
	s_nop 0
	global_load_lds_dwordx4 v[228:229], off
	s_mov_b32 m0, s23
	s_nop 0
	global_load_lds_dwordx4 v[230:231], off
	s_waitcnt vmcnt(8)
	s_waitcnt lgkmcnt(0)
	s_barrier
; #define PG8_STAGE(bufoff, gbase, voff) do { _Pragma("unroll") for (int _i = 0; _i < 2; ++_i) \
;         __builtin_amdgcn_global_load_lds((const unsigned*)((const char*)(gbase) + (voff)[_i]), (LAS unsigned*)(lds + (bufoff) + ldsw + _i * 8192), 16, 0, 0); } while (0)
; #define PG8_LDA(dst, b, h) do { _Pragma("unroll") for (int m = 0; m < 4; ++m) _Pragma("unroll") for (int k = 0; k < 2; ++k) dst[m][k] = *(const LAS bf16x8*)(lds + PG8_SA(b, h) + aoff + m * 2048 + k * 1024); } while (0)
; #define PG8_LDB(dst, b, h) do { _Pragma("unroll") for (int n = 0; n < 2; ++n) _Pragma("unroll") for (int k = 0; k < 2; ++k) dst[n][k] = *(const LAS bf16x8*)(lds + PG8_SB(b, h) + boff + n * 2048 + k * 1024); } while (0)
; #define PG8_MMA(ai, bj, At, Bt) do { __builtin_amdgcn_s_setprio(1); _Pragma("unroll") for (int m = 0; m < 4; ++m) _Pragma("unroll") for (int n = 0; n < 2; ++n) _Pragma("unroll") for (int k = 0; k < 2; ++k) \
;         acc[ai][bj][m][n] = __builtin_amdgcn_mfma_f32_16x16x32_bf16(Bt[n][k], At[m][k], acc[ai][bj][m][n], 0, 0, 0); __builtin_amdgcn_s_setprio(0); } while (0)
; #define PG8_WAIT_V(n) asm volatile("s_waitcnt vmcnt(" #n ")" ::: "memory")
; #define PG8_WAIT_L(n) asm volatile("s_waitcnt lgkmcnt(" #n ")" ::: "memory")
; #define PG8_BAR __builtin_amdgcn_s_barrier()
; #define PG8_SCHED __builtin_amdgcn_sched_barrier(0)
; template <class Epi>
; __device__ __forceinline__ void gemm_phase(LAS unsigned char* lds, const Gemm g, const StaticOrder& S, const Epi& E) {
;     ...
;             PG8_WAIT_V(8); PG8_WAIT_L(0); PG8_BAR; PG8_MMA(1, 0, At, B0); PG8_MMA(1, 1, At, B1); PG8_BAR; PG8_SCHED;
;             PG8_LDB(B0, 1, 0); PG8_LDB(B1, 1, 1); PG8_SCHED; PG8_LDA(At, 1, 0); PG8_STAGE(PG8_SA(0, 1), a2 + hstepA, voffA);
;             PG8_WAIT_V(8); PG8_WAIT_L(0); PG8_BAR; PG8_MMA(0, 0, At, B0); PG8_MMA(0, 1, At, B1); PG8_BAR; PG8_SCHED;
;             PG8_LDA(At, 1, 1); PG8_STAGE(PG8_SB(1, 0), b3, voffB); PG8_STAGE(PG8_SB(1, 1), b3 + hstepB, voffB); PG8_STAGE(PG8_SA(1, 0), a3, voffA);
;             PG8_WAIT_V(8); PG8_WAIT_L(0); PG8_BAR; PG8_MMA(1, 0, At, B0); PG8_MMA(1, 1, At, B1); PG8_BAR; PG8_SCHED;
	s_waitcnt lgkmcnt(0)
	v_mfma_f32_16x16x32_bf16 v[60:63], v[146:149], v[190:193], 0
	v_mfma_f32_16x16x32_bf16 v[52:55], v[164:167], v[190:193], 0
	v_mfma_f32_16x16x32_bf16 v[44:47], v[146:149], v[202:205], 0
	v_mfma_f32_16x16x32_bf16 v[36:39], v[164:167], v[202:205], 0
	v_mfma_f32_16x16x32_bf16 v[28:31], v[146:149], v[210:213], 0
	v_mfma_f32_16x16x32_bf16 v[20:23], v[164:167], v[210:213], 0
	v_mfma_f32_16x16x32_bf16 v[12:15], v[146:149], v[218:221], 0
	v_mfma_f32_16x16x32_bf16 v[4:7], v[164:167], v[218:221], 0
	v_mfma_f32_16x16x32_bf16 v[60:63], v[160:163], v[198:201], v[60:63]
	v_mfma_f32_16x16x32_bf16 v[52:55], v[168:171], v[198:201], v[52:55]
	v_mfma_f32_16x16x32_bf16 v[44:47], v[160:163], v[206:209], v[44:47]
	v_mfma_f32_16x16x32_bf16 v[36:39], v[168:171], v[206:209], v[36:39]
	v_mfma_f32_16x16x32_bf16 v[28:31], v[160:163], v[214:217], v[28:31]
	v_mfma_f32_16x16x32_bf16 v[20:23], v[168:171], v[214:217], v[20:23]
	v_mfma_f32_16x16x32_bf16 v[12:15], v[160:163], v[222:225], v[12:15]
	v_mfma_f32_16x16x32_bf16 v[4:7], v[168:171], v[222:225], v[4:7]
	v_mfma_f32_16x16x32_bf16 v[56:59], v[172:175], v[190:193], 0
	v_mfma_f32_16x16x32_bf16 v[48:51], v[180:183], v[190:193], 0
	v_mfma_f32_16x16x32_bf16 v[40:43], v[172:175], v[202:205], 0
	v_mfma_f32_16x16x32_bf16 v[32:35], v[180:183], v[202:205], 0
	v_mfma_f32_16x16x32_bf16 v[24:27], v[172:175], v[210:213], 0
	v_mfma_f32_16x16x32_bf16 v[16:19], v[180:183], v[210:213], 0
	v_mfma_f32_16x16x32_bf16 v[8:11], v[172:175], v[218:221], 0
	v_mfma_f32_16x16x32_bf16 v[0:3], v[180:183], v[218:221], 0
	v_mfma_f32_16x16x32_bf16 v[56:59], v[176:179], v[198:201], v[56:59]
	v_mfma_f32_16x16x32_bf16 v[48:51], v[184:187], v[198:201], v[48:51]
	v_mfma_f32_16x16x32_bf16 v[40:43], v[176:179], v[206:209], v[40:43]
	v_mfma_f32_16x16x32_bf16 v[32:35], v[184:187], v[206:209], v[32:35]
	v_mfma_f32_16x16x32_bf16 v[24:27], v[176:179], v[214:217], v[24:27]
	v_mfma_f32_16x16x32_bf16 v[16:19], v[184:187], v[214:217], v[16:19]
	v_mfma_f32_16x16x32_bf16 v[8:11], v[176:179], v[222:225], v[8:11]
	v_mfma_f32_16x16x32_bf16 v[0:3], v[184:187], v[222:225], v[0:3]
	s_barrier
	s_add_i32 s49, 0, 0x18000
	v_add_u32_e32 v136, s49, v151
	s_add_i32 s50, 0, 0x1c000
	ds_read_b128 v[146:149], v136
	ds_read_b128 v[160:163], v136 offset:1024
	ds_read_b128 v[164:167], v136 offset:2048
	ds_read_b128 v[168:171], v136 offset:3072
	v_add_u32_e32 v136, s50, v151
	ds_read_b128 v[172:175], v136
	ds_read_b128 v[176:179], v136 offset:1024
	ds_read_b128 v[180:183], v136 offset:2048
	ds_read_b128 v[184:187], v136 offset:3072
	s_add_u32 s18, s18, 0x40000
	s_addc_u32 s19, s19, 0
	s_mov_b32 m0, s24
	v_lshl_add_u64 v[232:233], s[18:19], 0, v[134:135]
	ds_read_b128 v[190:193], v155 offset:32768
	ds_read_b128 v[198:201], v155 offset:33792
	ds_read_b128 v[202:205], v155 offset:34816
	ds_read_b128 v[206:209], v155 offset:35840
	ds_read_b128 v[210:213], v155 offset:36864
	ds_read_b128 v[214:217], v155 offset:37888
	ds_read_b128 v[218:221], v155 offset:38912
	ds_read_b128 v[222:225], v155 offset:39936
	global_load_lds_dwordx4 v[232:233], off
	v_lshl_add_u64 v[232:233], s[18:19], 0, v[130:131]
	s_mov_b32 m0, s25
	s_nop 0
	global_load_lds_dwordx4 v[232:233], off
	s_waitcnt vmcnt(8)
	s_waitcnt lgkmcnt(0)
	s_barrier
	s_waitcnt lgkmcnt(0)
	v_mfma_f32_16x16x32_bf16 v[124:127], v[146:149], v[190:193], v[124:127]
	v_mfma_f32_16x16x32_bf16 v[116:119], v[164:167], v[190:193], v[116:119]
	v_mfma_f32_16x16x32_bf16 v[108:111], v[146:149], v[202:205], v[108:111]
	v_mfma_f32_16x16x32_bf16 v[100:103], v[164:167], v[202:205], v[100:103]
	v_mfma_f32_16x16x32_bf16 v[92:95], v[146:149], v[210:213], v[92:95]
	v_mfma_f32_16x16x32_bf16 v[84:87], v[164:167], v[210:213], v[84:87]
	v_mfma_f32_16x16x32_bf16 v[76:79], v[146:149], v[218:221], v[76:79]
	v_mfma_f32_16x16x32_bf16 v[68:71], v[164:167], v[218:221], v[68:71]
	v_mfma_f32_16x16x32_bf16 v[124:127], v[160:163], v[198:201], v[124:127]
	v_mfma_f32_16x16x32_bf16 v[116:119], v[168:171], v[198:201], v[116:119]
	v_mfma_f32_16x16x32_bf16 v[108:111], v[160:163], v[206:209], v[108:111]
	v_mfma_f32_16x16x32_bf16 v[100:103], v[168:171], v[206:209], v[100:103]
	v_mfma_f32_16x16x32_bf16 v[92:95], v[160:163], v[214:217], v[92:95]
	v_mfma_f32_16x16x32_bf16 v[84:87], v[168:171], v[214:217], v[84:87]
	v_mfma_f32_16x16x32_bf16 v[76:79], v[160:163], v[222:225], v[76:79]
	v_mfma_f32_16x16x32_bf16 v[68:71], v[168:171], v[222:225], v[68:71]
	v_mfma_f32_16x16x32_bf16 v[120:123], v[172:175], v[190:193], v[120:123]
	v_mfma_f32_16x16x32_bf16 v[112:115], v[180:183], v[190:193], v[112:115]
	v_mfma_f32_16x16x32_bf16 v[104:107], v[172:175], v[202:205], v[104:107]
	v_mfma_f32_16x16x32_bf16 v[96:99], v[180:183], v[202:205], v[96:99]
	v_mfma_f32_16x16x32_bf16 v[88:91], v[172:175], v[210:213], v[88:91]
	v_mfma_f32_16x16x32_bf16 v[80:83], v[180:183], v[210:213], v[80:83]
	v_mfma_f32_16x16x32_bf16 v[72:75], v[172:175], v[218:221], v[72:75]
	v_mfma_f32_16x16x32_bf16 v[64:67], v[180:183], v[218:221], v[64:67]
	v_mfma_f32_16x16x32_bf16 v[120:123], v[176:179], v[198:201], v[120:123]
	v_mfma_f32_16x16x32_bf16 v[112:115], v[184:187], v[198:201], v[112:115]
	v_mfma_f32_16x16x32_bf16 v[104:107], v[176:179], v[206:209], v[104:107]
	v_mfma_f32_16x16x32_bf16 v[96:99], v[184:187], v[206:209], v[96:99]
	v_mfma_f32_16x16x32_bf16 v[88:91], v[176:179], v[214:217], v[88:91]
	v_mfma_f32_16x16x32_bf16 v[80:83], v[184:187], v[214:217], v[80:83]
	v_mfma_f32_16x16x32_bf16 v[72:75], v[176:179], v[222:225], v[72:75]
	v_mfma_f32_16x16x32_bf16 v[64:67], v[184:187], v[222:225], v[64:67]
	s_barrier
; #define PG8_STAGE(bufoff, gbase, voff) do { _Pragma("unroll") for (int _i = 0; _i < 2; ++_i) \
;         __builtin_amdgcn_global_load_lds((const unsigned*)((const char*)(gbase) + (voff)[_i]), (LAS unsigned*)(lds + (bufoff) + ldsw + _i * 8192), 16, 0, 0); } while (0)
; #define PG8_LDA(dst, b, h) do { _Pragma("unroll") for (int m = 0; m < 4; ++m) _Pragma("unroll") for (int k = 0; k < 2; ++k) dst[m][k] = *(const LAS bf16x8*)(lds + PG8_SA(b, h) + aoff + m * 2048 + k * 1024); } while (0)
; #define PG8_MMA(ai, bj, At, Bt) do { __builtin_amdgcn_s_setprio(1); _Pragma("unroll") for (int m = 0; m < 4; ++m) _Pragma("unroll") for (int n = 0; n < 2; ++n) _Pragma("unroll") for (int k = 0; k < 2; ++k) \
;         acc[ai][bj][m][n] = __builtin_amdgcn_mfma_f32_16x16x32_bf16(Bt[n][k], At[m][k], acc[ai][bj][m][n], 0, 0, 0); __builtin_amdgcn_s_setprio(0); } while (0)
; #define PG8_WAIT_V(n) asm volatile("s_waitcnt vmcnt(" #n ")" ::: "memory")
; #define PG8_WAIT_L(n) asm volatile("s_waitcnt lgkmcnt(" #n ")" ::: "memory")
; #define PG8_BAR __builtin_amdgcn_s_barrier()
; #define PG8_SCHED __builtin_amdgcn_sched_barrier(0)
; template <class Epi>
; __device__ __forceinline__ void gemm_phase(LAS unsigned char* lds, const Gemm g, const StaticOrder& S, const Epi& E) {
;     ...
;             PG8_LDA(At, 1, 1); PG8_STAGE(PG8_SB(1, 0), b3, voffB); PG8_STAGE(PG8_SB(1, 1), b3 + hstepB, voffB); PG8_STAGE(PG8_SA(1, 0), a3, voffA);
;             PG8_WAIT_V(8); PG8_WAIT_L(0); PG8_BAR; PG8_MMA(1, 0, At, B0); PG8_MMA(1, 1, At, B1); PG8_BAR; PG8_SCHED;
;         }
	s_add_i32 s18, s49, s20
	v_lshl_add_u64 v[194:195], v[194:195], 0, s[6:7]
	s_mov_b32 m0, s18
	ds_read_b128 v[190:193], v155 offset:49152
	ds_read_b128 v[198:201], v155 offset:50176
	ds_read_b128 v[202:205], v155 offset:51200
	ds_read_b128 v[206:209], v155 offset:52224
	ds_read_b128 v[210:213], v155 offset:53248
	ds_read_b128 v[214:217], v155 offset:54272
	ds_read_b128 v[218:221], v155 offset:55296
	ds_read_b128 v[222:225], v155 offset:56320
	global_load_lds_dwordx4 v[194:195], off
	s_add_i32 m0, s18, 0x2000
	s_add_u32 s2, s2, 0x40080
	v_lshl_add_u64 v[194:195], v[226:227], 0, s[6:7]
	s_addc_u32 s3, s3, 0
	s_add_i32 s18, s50, s20
	global_load_lds_dwordx4 v[194:195], off
	v_lshl_add_u64 v[194:195], s[2:3], 0, v[132:133]
	s_mov_b32 m0, s18
	s_nop 0
	global_load_lds_dwordx4 v[194:195], off
	v_lshl_add_u64 v[194:195], s[2:3], 0, v[128:129]
	s_add_i32 m0, s18, 0x2000
	s_nop 0
	global_load_lds_dwordx4 v[194:195], off
	v_lshl_add_u64 v[194:195], v[228:229], 0, s[6:7]
	s_mov_b32 m0, s30
	s_nop 0
	global_load_lds_dwordx4 v[194:195], off
	v_lshl_add_u64 v[194:195], v[230:231], 0, s[6:7]
	s_mov_b32 m0, s31
	s_nop 0
	global_load_lds_dwordx4 v[194:195], off
	s_waitcnt vmcnt(8)
	s_waitcnt lgkmcnt(0)
	s_barrier
	s_waitcnt lgkmcnt(0)
	v_mfma_f32_16x16x32_bf16 v[60:63], v[146:149], v[190:193], v[60:63]
	v_mfma_f32_16x16x32_bf16 v[52:55], v[164:167], v[190:193], v[52:55]
	v_mfma_f32_16x16x32_bf16 v[44:47], v[146:149], v[202:205], v[44:47]
	v_mfma_f32_16x16x32_bf16 v[36:39], v[164:167], v[202:205], v[36:39]
	v_mfma_f32_16x16x32_bf16 v[28:31], v[146:149], v[210:213], v[28:31]
	v_mfma_f32_16x16x32_bf16 v[20:23], v[164:167], v[210:213], v[20:23]
	v_mfma_f32_16x16x32_bf16 v[12:15], v[146:149], v[218:221], v[12:15]
	v_mfma_f32_16x16x32_bf16 v[4:7], v[164:167], v[218:221], v[4:7]
	v_mfma_f32_16x16x32_bf16 v[60:63], v[160:163], v[198:201], v[60:63]
	v_mfma_f32_16x16x32_bf16 v[52:55], v[168:171], v[198:201], v[52:55]
	v_mfma_f32_16x16x32_bf16 v[44:47], v[160:163], v[206:209], v[44:47]
	v_mfma_f32_16x16x32_bf16 v[36:39], v[168:171], v[206:209], v[36:39]
	v_mfma_f32_16x16x32_bf16 v[28:31], v[160:163], v[214:217], v[28:31]
	v_mfma_f32_16x16x32_bf16 v[20:23], v[168:171], v[214:217], v[20:23]
	v_mfma_f32_16x16x32_bf16 v[12:15], v[160:163], v[222:225], v[12:15]
	v_mfma_f32_16x16x32_bf16 v[4:7], v[168:171], v[222:225], v[4:7]
	v_mfma_f32_16x16x32_bf16 v[56:59], v[172:175], v[190:193], v[56:59]
	v_mfma_f32_16x16x32_bf16 v[48:51], v[180:183], v[190:193], v[48:51]
	v_mfma_f32_16x16x32_bf16 v[40:43], v[172:175], v[202:205], v[40:43]
	v_mfma_f32_16x16x32_bf16 v[32:35], v[180:183], v[202:205], v[32:35]
	v_mfma_f32_16x16x32_bf16 v[24:27], v[172:175], v[210:213], v[24:27]
	v_mfma_f32_16x16x32_bf16 v[16:19], v[180:183], v[210:213], v[16:19]
	v_mfma_f32_16x16x32_bf16 v[8:11], v[172:175], v[218:221], v[8:11]
	v_mfma_f32_16x16x32_bf16 v[0:3], v[180:183], v[218:221], v[0:3]
	v_mfma_f32_16x16x32_bf16 v[56:59], v[176:179], v[198:201], v[56:59]
	v_mfma_f32_16x16x32_bf16 v[48:51], v[184:187], v[198:201], v[48:51]
	v_mfma_f32_16x16x32_bf16 v[40:43], v[176:179], v[206:209], v[40:43]
	v_mfma_f32_16x16x32_bf16 v[32:35], v[184:187], v[206:209], v[32:35]
	v_mfma_f32_16x16x32_bf16 v[24:27], v[176:179], v[214:217], v[24:27]
	v_mfma_f32_16x16x32_bf16 v[16:19], v[184:187], v[214:217], v[16:19]
	v_mfma_f32_16x16x32_bf16 v[8:11], v[176:179], v[222:225], v[8:11]
	v_mfma_f32_16x16x32_bf16 v[0:3], v[184:187], v[222:225], v[0:3]
	s_barrier
	s_add_i32 s48, s48, 2
	s_add_u32 s16, s16, 0x100
	s_addc_u32 s17, s17, 0
	s_add_u32 s46, s46, 0x100
	s_addc_u32 s47, s47, 0
	s_cmp_gt_u32 s48, 13
	s_cbranch_scc0 .LBB0_929

; #define PG8_STAGE(bufoff, gbase, voff) do { _Pragma("unroll") for (int _i = 0; _i < 2; ++_i) \
;         __builtin_amdgcn_global_load_lds((const unsigned*)((const char*)(gbase) + (voff)[_i]), (LAS unsigned*)(lds + (bufoff) + ldsw + _i * 8192), 16, 0, 0); } while (0)
; #define PG8_WAIT_V(n) asm volatile("s_waitcnt vmcnt(" #n ")" ::: "memory")
; #define PG8_BAR __builtin_amdgcn_s_barrier()
; template <class Epi>
; __device__ __forceinline__ void gemm_phase(LAS unsigned char* lds, const Gemm g, const StaticOrder& S, const Epi& E) {
;     ...
;     const int wid = __builtin_amdgcn_readfirstlane(tid >> 6), lane = tid & 63, wr = wid >> 2, wc = wid & 3, fr = lane & 15, fq = lane >> 4;
;     const int K = g.K, nt = K / BK, lda = g.lda;
;     unsigned voffA[2], voffB[2];
; #pragma unroll
;     for (int i = 0; i < 2; ++i) { int R, C; stage_rc(tid * 16 + i * 8192, R, C); const int Rb = Epi::PERM ? ((R & ~31) + perm32(R & 31)) : R;
;         voffA[i] = (unsigned)(R * lda + C) * 2u; voffB[i] = (unsigned)(Rb * K + C) * 2u; }
;     const size_t kstep = (size_t)(BK * 2);
;     const size_t hstepA = (size_t)HALF * lda * 2, hstepB = (size_t)HALF * K * 2;
;     const size_t tstepA = 2 * hstepA, tstepB = 2 * hstepB;
;     const unsigned ldsw = (unsigned)wid * 1024u;
;     const int aoff = lds_byte(wr * 64 + fr, fq * 8), boff = lds_byte(wc * 32 + fr, fq * 8);
;     ...
;     PG8_STAGE(PG8_SB(0, 0), cB, voffB); PG8_STAGE(PG8_SB(0, 1), cB + hstepB, voffB); PG8_STAGE(PG8_SA(0, 0), cA, voffA); PG8_STAGE(PG8_SA(0, 1), cA + hstepA, voffA);
;     if (wr == 1) PG8_BAR;
;     PG8_WAIT_V(2); PG8_BAR;
;     PG8_STAGE(PG8_SB(1, 0), cB + kstep, voffB); PG8_STAGE(PG8_SA(1, 0), cA + kstep, voffA); PG8_STAGE(PG8_SB(1, 1), cB + hstepB + kstep, voffB);
;     PG8_WAIT_V(6); PG8_BAR;
.LBB0_1020:
	s_mov_b64 s[14:15], 0x80
	s_and_b32 s29, s1, 3
	s_add_i32 m0, s25, 0x18000
	v_lshl_add_u64 v[6:7], v[6:7], 0, s[14:15]
	s_lshl_b32 s1, s5, 13
	s_lshl_b32 s18, s29, 12
	global_load_lds_dwordx4 v[6:7], off
	v_lshl_add_u64 v[4:5], v[4:5], 0, s[14:15]
	s_add_i32 m0, s25, 0x1a000
	s_add_i32 s30, s25, 0x8000
	s_add_i32 s31, s25, 0xa000
	global_load_lds_dwordx4 v[4:5], off
	v_lshl_add_u64 v[0:1], v[0:1], 0, s[14:15]
	s_mov_b32 m0, s30
	s_add_u32 s6, s8, 0xb0080
	global_load_lds_dwordx4 v[0:1], off
	v_lshl_add_u64 v[0:1], v[2:3], 0, s[14:15]
	s_mov_b32 m0, s31
	s_addc_u32 s7, s9, 0
	global_load_lds_dwordx4 v[0:1], off
	s_add_i32 m0, s25, 0x1c000
	v_lshl_add_u64 v[0:1], s[6:7], 0, v[154:155]
	global_load_lds_dwordx4 v[0:1], off
	v_lshl_add_u64 v[0:1], s[6:7], 0, v[158:159]
	s_add_i32 m0, s25, 0x1e000
	s_cmpk_lt_u32 s4, 0x100
	global_load_lds_dwordx4 v[0:1], off
	s_waitcnt vmcnt(8)
	s_barrier
	v_and_b32_e32 v1, 15, v8
	v_lshl_or_b32 v184, s5, 6, v1
	v_readlane_b32 s5, v235, 0
	s_cselect_b64 s[16:17], -1, 0
	s_ashr_i32 s33, s74, 31
	s_ashr_i32 s4, s5, 31
	s_sub_u32 s6, 0x400, s5
	s_subb_u32 s7, 0, s4
	s_abs_i32 s19, s74
	v_bfe_u32 v0, v8, 4, 2
	v_cvt_f32_u32_e32 v4, s19
	v_lshlrev_b32_e32 v3, 4, v0
	v_lshl_or_b32 v1, v1, 6, v3
	v_lshlrev_b32_e32 v3, 2, v8
	v_and_b32_e32 v3, 32, v3
	v_bitop3_b32 v5, v1, s1, v3 bitop3:0xde
	v_bitop3_b32 v185, v1, s18, v3 bitop3:0xde
	v_rcp_iflag_f32_e32 v1, v4
	s_sub_i32 s1, 0, s19
	v_lshlrev_b32_e32 v2, 3, v0
	v_cmp_eq_u32_e64 s[4:5], 0, v0
	v_mul_f32_e32 v1, 0x4f7ffffe, v1
	v_cvt_u32_f32_e32 v1, v1
	v_mul_lo_u32 v0, v11, s0
	s_waitcnt vmcnt(6)
	v_lshl_or_b32 v186, s29, 5, v2
	v_readfirstlane_b32 s18, v1
	s_mul_i32 s1, s1, s18
	s_mul_hi_u32 s1, s18, s1
	s_add_i32 s18, s18, s1
	s_lshr_b32 s1, s18, 22
	s_mul_i32 s18, s1, s19
	s_sub_i32 s18, 0x400, s18
	s_add_i32 s20, s1, 1
	s_sub_i32 s21, s18, s19
	s_cmp_ge_u32 s18, s19
	s_cselect_b32 s1, s20, s1
	s_cselect_b32 s18, s21, s18
	s_add_i32 s20, s1, 1
	s_cmp_ge_u32 s18, s19
	s_cselect_b32 s1, s20, s1
	s_xor_b32 s1, s1, s33
	s_sub_i32 s35, s1, s33
	v_lshrrev_b32_e32 v1, 1, v9
	s_mov_b32 s1, 0xb400
	v_mad_u64_u32 v[0:1], s[18:19], v1, s1, v[0:1]
	v_or_b32_e32 v0, v0, v10
	v_add_lshl_u32 v0, v0, v12, 1
	v_mov_b32_e32 v1, v155
	s_mov_b64 s[18:19], 0xb4080
	v_lshl_add_u64 v[160:161], v[0:1], 0, s[18:19]
	v_lshrrev_b32_e32 v1, 1, v13
	v_mul_lo_u32 v0, v14, s0
	v_mad_u64_u32 v[0:1], s[0:1], v1, s1, v[0:1]
	v_or_b32_e32 v0, v0, v15
	v_add_lshl_u32 v0, v0, v16, 1
	v_mov_b32_e32 v1, v155
	v_lshl_add_u64 v[162:163], v[0:1], 0, s[18:19]
	s_add_i32 s36, 0, 0x10000
	s_add_i32 s37, 0, 0x14000
	v_mbcnt_lo_u32_b32 v0, -1, 0
	s_mov_b32 s34, s74
	v_mov_b64_e32 v[164:165], s[6:7]
	v_add_u32_e32 v187, s36, v185
	v_add_u32_e32 v188, s37, v185
	v_add_u32_e32 v190, 0, v5
	v_mbcnt_hi_u32_b32 v191, -1, v0
	s_mov_b32 s6, 0
	s_barrier
	s_branch .LBB0_1023

; #define PG8_STAGE(bufoff, gbase, voff) do { _Pragma("unroll") for (int _i = 0; _i < 2; ++_i) \
;         __builtin_amdgcn_global_load_lds((const unsigned*)((const char*)(gbase) + (voff)[_i]), (LAS unsigned*)(lds + (bufoff) + ldsw + _i * 8192), 16, 0, 0); } while (0)
; #define PG8_WAIT_V(n) asm volatile("s_waitcnt vmcnt(" #n ")" ::: "memory")
; #define PG8_BAR __builtin_amdgcn_s_barrier()
; template <class Epi>
; __device__ __forceinline__ void gemm_phase(LAS unsigned char* lds, const Gemm g, const StaticOrder& S, const Epi& E) {
;     ...
;     const int wid = __builtin_amdgcn_readfirstlane(tid >> 6), lane = tid & 63, wr = wid >> 2, wc = wid & 3, fr = lane & 15, fq = lane >> 4;
;     const int K = g.K, nt = K / BK, lda = g.lda;
;     unsigned voffA[2], voffB[2];
; #pragma unroll
;     for (int i = 0; i < 2; ++i) { int R, C; stage_rc(tid * 16 + i * 8192, R, C); const int Rb = Epi::PERM ? ((R & ~31) + perm32(R & 31)) : R;
;         voffA[i] = (unsigned)(R * lda + C) * 2u; voffB[i] = (unsigned)(Rb * K + C) * 2u; }
;     const size_t kstep = (size_t)(BK * 2);
;     const size_t hstepA = (size_t)HALF * lda * 2, hstepB = (size_t)HALF * K * 2;
;     const size_t tstepA = 2 * hstepA, tstepB = 2 * hstepB;
;     const unsigned ldsw = (unsigned)wid * 1024u;
;     const int aoff = lds_byte(wr * 64 + fr, fq * 8), boff = lds_byte(wc * 32 + fr, fq * 8);
;     ...
;     PG8_STAGE(PG8_SB(0, 0), cB, voffB); PG8_STAGE(PG8_SB(0, 1), cB + hstepB, voffB); PG8_STAGE(PG8_SA(0, 0), cA, voffA); PG8_STAGE(PG8_SA(0, 1), cA + hstepA, voffA);
;     if (wr == 1) PG8_BAR;
;     PG8_WAIT_V(2); PG8_BAR;
;     PG8_STAGE(PG8_SB(1, 0), cB + kstep, voffB); PG8_STAGE(PG8_SA(1, 0), cA + kstep, voffA); PG8_STAGE(PG8_SB(1, 1), cB + hstepB + kstep, voffB);
;     PG8_WAIT_V(6); PG8_BAR;
.LBB0_1163:
	s_add_u32 s31, s72, 0x908000
	s_mov_b64 s[14:15], 0x80
	s_addc_u32 s33, s73, 0
	s_and_b32 s10, s0, 3
	s_add_i32 m0, s27, 0x18000
	v_lshl_add_u64 v[6:7], v[6:7], 0, s[14:15]
	s_lshl_b32 s0, s1, 13
	s_lshl_b32 s8, s10, 12
	global_load_lds_dwordx4 v[6:7], off
	v_lshl_add_u64 v[4:5], v[4:5], 0, s[14:15]
	s_add_i32 m0, s27, 0x1a000
	s_add_i32 s34, s27, 0x8000
	s_add_i32 s35, s27, 0xa000
	global_load_lds_dwordx4 v[4:5], off
	v_lshl_add_u64 v[0:1], v[0:1], 0, s[14:15]
	s_mov_b32 m0, s34
	s_add_u32 s6, s20, 0xb0080
	global_load_lds_dwordx4 v[0:1], off
	v_lshl_add_u64 v[0:1], v[2:3], 0, s[14:15]
	s_mov_b32 m0, s35
	s_addc_u32 s7, s21, 0
	global_load_lds_dwordx4 v[0:1], off
	s_add_i32 m0, s27, 0x1c000
	v_lshl_add_u64 v[0:1], s[6:7], 0, v[154:155]
	global_load_lds_dwordx4 v[0:1], off
	v_lshl_add_u64 v[0:1], s[6:7], 0, v[158:159]
	s_add_i32 m0, s27, 0x1e000
	v_bfe_u32 v2, v8, 4, 2
	global_load_lds_dwordx4 v[0:1], off
	s_waitcnt vmcnt(8)
	s_barrier
	s_cmpk_lt_u32 s4, 0x100
	v_readlane_b32 s6, v235, 0
	v_and_b32_e32 v1, 15, v8
	v_lshlrev_b32_e32 v0, 4, v2
	v_lshlrev_b32_e32 v4, 2, v8
	s_cselect_b64 s[16:17], -1, 0
	s_ashr_i32 s4, s6, 31
	v_lshl_or_b32 v197, s1, 6, v1
	v_lshl_or_b32 v1, v1, 6, v0
	v_and_b32_e32 v4, 32, v4
	s_sub_u32 s6, 0x400, s6
	v_readlane_b32 s18, v235, 50
	v_bitop3_b32 v5, v1, s0, v4 bitop3:0xde
	v_bitop3_b32 v198, v1, s8, v4 bitop3:0xde
	s_subb_u32 s7, 0, s4
	s_lshl_b32 s4, s10, 2
	v_readlane_b32 s19, v235, 51
	v_mov_b32_e32 v1, v155
	s_add_u32 s36, s18, s4
	v_lshl_add_u64 v[160:161], s[18:19], 0, v[0:1]
	v_lshrrev_b32_e32 v1, 1, v9
	v_mul_lo_u32 v0, v11, s5
	s_mov_b32 s4, 0xb400
	s_addc_u32 s37, s19, 0
	v_mad_u64_u32 v[0:1], s[18:19], v1, s4, v[0:1]
	v_or_b32_e32 v0, v0, v10
	v_add_lshl_u32 v0, v0, v12, 1
	v_mov_b32_e32 v1, v155
	s_mov_b64 s[18:19], 0xb4080
	v_lshl_add_u64 v[162:163], v[0:1], 0, s[18:19]
	v_lshrrev_b32_e32 v1, 1, v13
	v_mul_lo_u32 v0, v14, s5
	v_mad_u64_u32 v[0:1], s[4:5], v1, s4, v[0:1]
	v_or_b32_e32 v0, v0, v15
	s_waitcnt vmcnt(6)
	v_add_lshl_u32 v0, v0, v16, 1
	v_mov_b32_e32 v1, v155
	v_lshlrev_b32_e32 v3, 3, v2
	v_lshl_add_u64 v[164:165], v[0:1], 0, s[18:19]
	s_add_i32 s38, 0, 0x10000
	s_add_i32 s39, 0, 0x14000
	v_mbcnt_lo_u32_b32 v0, -1, 0
	v_lshl_or_b32 v199, s10, 5, v3
	v_cmp_eq_u32_e64 s[0:1], 0, v2
	v_cmp_eq_u32_e64 s[8:9], 0, v189
	v_mov_b64_e32 v[166:167], s[6:7]
	v_add_u32_e32 v200, s38, v198
	v_add_u32_e32 v201, s39, v198
	v_add_u32_e32 v202, 0, v5
	v_mbcnt_hi_u32_b32 v203, -1, v0
	v_mov_b32_e32 v204, 0x358637bd
	s_mov_b32 s4, 0
	s_barrier
	s_branch .LBB0_1166
